# GEMM tile boundary (7 of 14 instances): leading half starts its epilogue without waiting for the trailing half's last MFMA block; trailing half's epilogue runs before its last rendezvous
# speedup vs baseline: 1.0093x; 1.0033x over previous
; #define PG8_STAGE(bufoff, gbase, voff) do { _Pragma("unroll") for (int _i = 0; _i < 2; ++_i) \
;         __builtin_amdgcn_global_load_lds((const unsigned*)((const char*)(gbase) + (voff)[_i]), (PG8_LAS unsigned*)(lds + (bufoff) + ldsw + _i * 8192), 16, 0, 0); } while (0)
; #define PG8_LDA(dst, b, h) do { _Pragma("unroll") for (int m = 0; m < 4; ++m) _Pragma("unroll") for (int k = 0; k < 2; ++k) dst[m][k] = *(const PG8_LAS bf16x8*)(lds + PG8_SA(b, h) + aoff + m * 2048 + k * 1024); } while (0)
; #define PG8_LDB(dst, b, h) do { _Pragma("unroll") for (int n = 0; n < 2; ++n) _Pragma("unroll") for (int k = 0; k < 2; ++k) dst[n][k] = *(const PG8_LAS bf16x8*)(lds + PG8_SB(b, h) + boff + n * 2048 + k * 1024); } while (0)
; #define PG8_MMA(ai, bj, At, Bt) do { __builtin_amdgcn_s_setprio(1); _Pragma("unroll") for (int m = 0; m < 4; ++m) _Pragma("unroll") for (int n = 0; n < 2; ++n) _Pragma("unroll") for (int k = 0; k < 2; ++k) \
;         acc[ai][bj][m][n] = __builtin_amdgcn_mfma_f32_16x16x32_bf16(Bt[n][k], At[m][k], acc[ai][bj][m][n], 0, 0, 0); __builtin_amdgcn_s_setprio(0); } while (0)
; #define PG8_WAIT_V(n) asm volatile("s_waitcnt vmcnt(" #n ")" ::: "memory")
; #define PG8_WAIT_L(n) asm volatile("s_waitcnt lgkmcnt(" #n ")" ::: "memory")
; template <class Epi, class Sched, bool ALIGN_EPI = false, bool SP2 = false>
; __device__ __forceinline__ void gemm_phase(PG8_LAS unsigned char* lds, const Gemm g, const Sched& S, const Epi& E) {
;     ...
;             const bool last = (t == nt - 2);
;             const char* a1 = cA + (size_t)(t + 1) * kstep;
;             const char* a2 = last ? nA : cA + (size_t)(t + 2) * kstep; const char* b2 = last ? nB : cB + (size_t)(t + 2) * kstep;
;             const char* a3 = a2 + kstep; const char* b3 = b2 + kstep;
;             if (last && has_next) S.a_ready(nxt);
;             if constexpr (SP2) {
;             PG8_LDB(B0, 0, 0); PG8_LDB(B1, 0, 1); PG8_SCHED; PG8_LDA(At, 0, 0); PG8_STAGE(PG8_SA(1, 1), a1 + hstep, voffA);
;             PG8_WAIT_V(8); PG8_WAIT_L(0); PG8_BAR; PG8_MMA(0, 0, At, B0); PG8_MMA(0, 1, At, B1); PG8_BAR; PG8_SCHED;
;             PG8_LDA(At, 0, 1); PG8_STAGE(PG8_SB(0, 0), b2, voffB); PG8_STAGE(PG8_SB(0, 1), b2 + hstep, voffB); PG8_STAGE(PG8_SA(0, 0), a2, voffA);
;             PG8_WAIT_V(8); PG8_WAIT_L(0); PG8_BAR; PG8_MMA(1, 0, At, B0); PG8_MMA(1, 1, At, B1); PG8_BAR; PG8_SCHED;
.LBB0_224:
	ds_read_b128 v[154:157], v150
	ds_read_b128 v[158:161], v150 offset:1024
	ds_read_b128 v[162:165], v150 offset:2048
	ds_read_b128 v[166:169], v150 offset:3072
	ds_read_b128 v[170:173], v151
	ds_read_b128 v[174:177], v151 offset:1024
	ds_read_b128 v[178:181], v151 offset:2048
	ds_read_b128 v[182:185], v151 offset:3072
	s_add_u32 s42, s20, 0xfffc0080
	s_addc_u32 s43, s21, -1
	s_cmp_eq_u32 s72, 12
	s_cselect_b32 s47, s15, s43
	s_cselect_b32 s46, s68, s42
	s_cselect_b32 s43, s13, s71
	s_cselect_b32 s42, s69, s70
	s_add_i32 m0, s35, 0xc000
	ds_read_b128 v[186:189], v152
	ds_read_b128 v[190:193], v152 offset:1024
	ds_read_b128 v[198:201], v152 offset:2048
	ds_read_b128 v[202:205], v152 offset:3072
	ds_read_b128 v[206:209], v152 offset:4096
	ds_read_b128 v[210:213], v152 offset:5120
	ds_read_b128 v[214:217], v152 offset:6144
	ds_read_b128 v[218:221], v152 offset:7168
	global_load_lds_dwordx4 v136, s[20:21]
	s_add_i32 m0, s35, 0xe000
	s_nop 0
	global_load_lds_dwordx4 v138, s[20:21]
	s_waitcnt vmcnt(8)
	s_waitcnt lgkmcnt(0)
	s_barrier
	v_mfma_f32_16x16x32_bf16 v[124:127], v[154:157], v[186:189], v[124:127]
	v_mfma_f32_16x16x32_bf16 v[116:119], v[162:165], v[186:189], v[116:119]
	v_mfma_f32_16x16x32_bf16 v[108:111], v[154:157], v[198:201], v[108:111]
	v_mfma_f32_16x16x32_bf16 v[100:103], v[162:165], v[198:201], v[100:103]
	v_mfma_f32_16x16x32_bf16 v[92:95], v[154:157], v[206:209], v[92:95]
	v_mfma_f32_16x16x32_bf16 v[84:87], v[162:165], v[206:209], v[84:87]
	v_mfma_f32_16x16x32_bf16 v[76:79], v[154:157], v[214:217], v[76:79]
	v_mfma_f32_16x16x32_bf16 v[68:71], v[162:165], v[214:217], v[68:71]
	v_mfma_f32_16x16x32_bf16 v[124:127], v[158:161], v[190:193], v[124:127]
	v_mfma_f32_16x16x32_bf16 v[116:119], v[166:169], v[190:193], v[116:119]
	v_mfma_f32_16x16x32_bf16 v[108:111], v[158:161], v[202:205], v[108:111]
	v_mfma_f32_16x16x32_bf16 v[100:103], v[166:169], v[202:205], v[100:103]
	v_mfma_f32_16x16x32_bf16 v[92:95], v[158:161], v[210:213], v[92:95]
	v_mfma_f32_16x16x32_bf16 v[84:87], v[166:169], v[210:213], v[84:87]
	v_mfma_f32_16x16x32_bf16 v[76:79], v[158:161], v[218:221], v[76:79]
	v_mfma_f32_16x16x32_bf16 v[68:71], v[166:169], v[218:221], v[68:71]
	v_mfma_f32_16x16x32_bf16 v[120:123], v[170:173], v[186:189], v[120:123]
	v_mfma_f32_16x16x32_bf16 v[112:115], v[178:181], v[186:189], v[112:115]
	v_mfma_f32_16x16x32_bf16 v[104:107], v[170:173], v[198:201], v[104:107]
	v_mfma_f32_16x16x32_bf16 v[96:99], v[178:181], v[198:201], v[96:99]
	v_mfma_f32_16x16x32_bf16 v[88:91], v[170:173], v[206:209], v[88:91]
	v_mfma_f32_16x16x32_bf16 v[80:83], v[178:181], v[206:209], v[80:83]
	v_mfma_f32_16x16x32_bf16 v[72:75], v[170:173], v[214:217], v[72:75]
	v_mfma_f32_16x16x32_bf16 v[64:67], v[178:181], v[214:217], v[64:67]
	v_mfma_f32_16x16x32_bf16 v[120:123], v[174:177], v[190:193], v[120:123]
	v_mfma_f32_16x16x32_bf16 v[112:115], v[182:185], v[190:193], v[112:115]
	v_mfma_f32_16x16x32_bf16 v[104:107], v[174:177], v[202:205], v[104:107]
	v_mfma_f32_16x16x32_bf16 v[96:99], v[182:185], v[202:205], v[96:99]
	v_mfma_f32_16x16x32_bf16 v[88:91], v[174:177], v[210:213], v[88:91]
	v_mfma_f32_16x16x32_bf16 v[80:83], v[182:185], v[210:213], v[80:83]
	v_mfma_f32_16x16x32_bf16 v[72:75], v[174:177], v[218:221], v[72:75]
	v_mfma_f32_16x16x32_bf16 v[64:67], v[182:185], v[218:221], v[64:67]
	s_barrier
	s_add_i32 s73, s63, s55
	s_add_u32 s98, s42, s8
	s_addc_u32 s99, s43, s9
	s_add_u32 s100, s46, s8
	s_addc_u32 s101, s47, s9
	s_mov_b32 m0, s73
	ds_read_b128 v[186:189], v152 offset:16384
	ds_read_b128 v[190:193], v152 offset:17408
	ds_read_b128 v[198:201], v152 offset:18432
	ds_read_b128 v[202:205], v152 offset:19456
	ds_read_b128 v[206:209], v152 offset:20480
	ds_read_b128 v[210:213], v152 offset:21504
	ds_read_b128 v[214:217], v152 offset:22528
	ds_read_b128 v[218:221], v152 offset:23552
	global_load_lds_dwordx4 v132, s[42:43]
	s_add_i32 m0, s73, 0x2000
	s_add_u32 s74, s42, 0x40000
	s_addc_u32 s75, s43, 0
	s_add_i32 s73, s64, s55
	global_load_lds_dwordx4 v128, s[42:43]
	s_mov_b32 m0, s73
	s_nop 0
	global_load_lds_dwordx4 v132, s[74:75]
	s_add_i32 m0, s73, 0x2000
	s_nop 0
	global_load_lds_dwordx4 v128, s[74:75]
	s_mov_b32 m0, s35
	s_nop 0
	global_load_lds_dwordx4 v134, s[46:47]
	s_mov_b32 m0, s57
	s_nop 0
	global_load_lds_dwordx4 v130, s[46:47]
	s_waitcnt vmcnt(8)
	s_waitcnt lgkmcnt(0)
	s_barrier
	v_mfma_f32_16x16x32_bf16 v[60:63], v[154:157], v[186:189], v[60:63]
	v_mfma_f32_16x16x32_bf16 v[52:55], v[162:165], v[186:189], v[52:55]
	v_mfma_f32_16x16x32_bf16 v[44:47], v[154:157], v[198:201], v[44:47]
	v_mfma_f32_16x16x32_bf16 v[36:39], v[162:165], v[198:201], v[36:39]
	v_mfma_f32_16x16x32_bf16 v[28:31], v[154:157], v[206:209], v[28:31]
	v_mfma_f32_16x16x32_bf16 v[20:23], v[162:165], v[206:209], v[20:23]
	v_mfma_f32_16x16x32_bf16 v[12:15], v[154:157], v[214:217], v[12:15]
	v_mfma_f32_16x16x32_bf16 v[4:7], v[162:165], v[214:217], v[4:7]
	v_mfma_f32_16x16x32_bf16 v[60:63], v[158:161], v[190:193], v[60:63]
	v_mfma_f32_16x16x32_bf16 v[52:55], v[166:169], v[190:193], v[52:55]
	v_mfma_f32_16x16x32_bf16 v[44:47], v[158:161], v[202:205], v[44:47]
	v_mfma_f32_16x16x32_bf16 v[36:39], v[166:169], v[202:205], v[36:39]
	v_mfma_f32_16x16x32_bf16 v[28:31], v[158:161], v[210:213], v[28:31]
	v_mfma_f32_16x16x32_bf16 v[20:23], v[166:169], v[210:213], v[20:23]
	v_mfma_f32_16x16x32_bf16 v[12:15], v[158:161], v[218:221], v[12:15]
	v_mfma_f32_16x16x32_bf16 v[4:7], v[166:169], v[218:221], v[4:7]
	v_mfma_f32_16x16x32_bf16 v[56:59], v[170:173], v[186:189], v[56:59]
	v_mfma_f32_16x16x32_bf16 v[48:51], v[178:181], v[186:189], v[48:51]
	v_mfma_f32_16x16x32_bf16 v[40:43], v[170:173], v[198:201], v[40:43]
	v_mfma_f32_16x16x32_bf16 v[32:35], v[178:181], v[198:201], v[32:35]
	v_mfma_f32_16x16x32_bf16 v[24:27], v[170:173], v[206:209], v[24:27]
	v_mfma_f32_16x16x32_bf16 v[16:19], v[178:181], v[206:209], v[16:19]
	v_mfma_f32_16x16x32_bf16 v[8:11], v[170:173], v[214:217], v[8:11]
	v_mfma_f32_16x16x32_bf16 v[0:3], v[178:181], v[214:217], v[0:3]
	v_mfma_f32_16x16x32_bf16 v[56:59], v[174:177], v[190:193], v[56:59]
	v_mfma_f32_16x16x32_bf16 v[48:51], v[182:185], v[190:193], v[48:51]
	v_mfma_f32_16x16x32_bf16 v[40:43], v[174:177], v[202:205], v[40:43]
	v_mfma_f32_16x16x32_bf16 v[32:35], v[182:185], v[202:205], v[32:35]
	v_mfma_f32_16x16x32_bf16 v[24:27], v[174:177], v[210:213], v[24:27]
	v_mfma_f32_16x16x32_bf16 v[16:19], v[182:185], v[210:213], v[16:19]
	v_mfma_f32_16x16x32_bf16 v[8:11], v[174:177], v[218:221], v[8:11]
	v_mfma_f32_16x16x32_bf16 v[0:3], v[182:185], v[218:221], v[0:3]
	s_barrier
; #define PG8_STAGE(bufoff, gbase, voff) do { _Pragma("unroll") for (int _i = 0; _i < 2; ++_i) \
;         __builtin_amdgcn_global_load_lds((const unsigned*)((const char*)(gbase) + (voff)[_i]), (PG8_LAS unsigned*)(lds + (bufoff) + ldsw + _i * 8192), 16, 0, 0); } while (0)
; #define PG8_LDA(dst, b, h) do { _Pragma("unroll") for (int m = 0; m < 4; ++m) _Pragma("unroll") for (int k = 0; k < 2; ++k) dst[m][k] = *(const PG8_LAS bf16x8*)(lds + PG8_SA(b, h) + aoff + m * 2048 + k * 1024); } while (0)
; #define PG8_LDB(dst, b, h) do { _Pragma("unroll") for (int n = 0; n < 2; ++n) _Pragma("unroll") for (int k = 0; k < 2; ++k) dst[n][k] = *(const PG8_LAS bf16x8*)(lds + PG8_SB(b, h) + boff + n * 2048 + k * 1024); } while (0)
; #define PG8_MMA(ai, bj, At, Bt) do { __builtin_amdgcn_s_setprio(1); _Pragma("unroll") for (int m = 0; m < 4; ++m) _Pragma("unroll") for (int n = 0; n < 2; ++n) _Pragma("unroll") for (int k = 0; k < 2; ++k) \
;         acc[ai][bj][m][n] = __builtin_amdgcn_mfma_f32_16x16x32_bf16(Bt[n][k], At[m][k], acc[ai][bj][m][n], 0, 0, 0); __builtin_amdgcn_s_setprio(0); } while (0)
; #define PG8_WAIT_V(n) asm volatile("s_waitcnt vmcnt(" #n ")" ::: "memory")
; #define PG8_WAIT_L(n) asm volatile("s_waitcnt lgkmcnt(" #n ")" ::: "memory")
; #define PG8_BAR __builtin_amdgcn_s_barrier()
; #define PG8_SCHED __builtin_amdgcn_sched_barrier(0)
; template <class Epi, class Sched, bool ALIGN_EPI = false, bool SP2 = false>
; __device__ __forceinline__ void gemm_phase(PG8_LAS unsigned char* lds, const Gemm g, const Sched& S, const Epi& E) {
;     ...
;             PG8_LDB(B0, 1, 0); PG8_LDB(B1, 1, 1); PG8_SCHED; PG8_LDA(At, 1, 0); PG8_STAGE(PG8_SA(0, 1), a2 + hstep, voffA);
;             PG8_WAIT_V(8); PG8_WAIT_L(0); PG8_BAR; PG8_MMA(0, 0, At, B0); PG8_MMA(0, 1, At, B1); PG8_BAR; PG8_SCHED;
;             PG8_LDA(At, 1, 1); PG8_STAGE(PG8_SB(1, 0), b3, voffB); PG8_STAGE(PG8_SB(1, 1), b3 + hstep, voffB); PG8_STAGE(PG8_SA(1, 0), a3, voffA);
;             PG8_WAIT_V(8); PG8_WAIT_L(0); PG8_BAR; PG8_MMA(1, 0, At, B0); PG8_MMA(1, 1, At, B1); PG8_BAR; PG8_SCHED;
;     ...
;         if constexpr (ALIGN_EPI) { if (wr == 0) PG8_BAR; }
	s_add_i32 s73, 0, 0x18000
	v_add_u32_e32 v153, s73, v147
	s_add_i32 s74, 0, 0x1c000
	ds_read_b128 v[154:157], v153
	ds_read_b128 v[158:161], v153 offset:1024
	ds_read_b128 v[162:165], v153 offset:2048
	ds_read_b128 v[166:169], v153 offset:3072
	v_add_u32_e32 v153, s74, v147
	ds_read_b128 v[170:173], v153
	ds_read_b128 v[174:177], v153 offset:1024
	ds_read_b128 v[178:181], v153 offset:2048
	ds_read_b128 v[182:185], v153 offset:3072
	s_add_u32 s46, s46, 0x40000
	s_addc_u32 s47, s47, 0
	s_mov_b32 m0, s58
	ds_read_b128 v[186:189], v152 offset:32768
	ds_read_b128 v[190:193], v152 offset:33792
	ds_read_b128 v[198:201], v152 offset:34816
	ds_read_b128 v[202:205], v152 offset:35840
	ds_read_b128 v[206:209], v152 offset:36864
	ds_read_b128 v[210:213], v152 offset:37888
	ds_read_b128 v[214:217], v152 offset:38912
	ds_read_b128 v[218:221], v152 offset:39936
	global_load_lds_dwordx4 v134, s[46:47]
	s_mov_b32 m0, s59
	s_nop 0
	global_load_lds_dwordx4 v130, s[46:47]
	s_waitcnt vmcnt(8)
	s_waitcnt lgkmcnt(0)
	s_barrier
	v_mfma_f32_16x16x32_bf16 v[124:127], v[154:157], v[186:189], v[124:127]
	v_mfma_f32_16x16x32_bf16 v[116:119], v[162:165], v[186:189], v[116:119]
	v_mfma_f32_16x16x32_bf16 v[108:111], v[154:157], v[198:201], v[108:111]
	v_mfma_f32_16x16x32_bf16 v[100:103], v[162:165], v[198:201], v[100:103]
	v_mfma_f32_16x16x32_bf16 v[92:95], v[154:157], v[206:209], v[92:95]
	v_mfma_f32_16x16x32_bf16 v[84:87], v[162:165], v[206:209], v[84:87]
	v_mfma_f32_16x16x32_bf16 v[76:79], v[154:157], v[214:217], v[76:79]
	v_mfma_f32_16x16x32_bf16 v[68:71], v[162:165], v[214:217], v[68:71]
	v_mfma_f32_16x16x32_bf16 v[124:127], v[158:161], v[190:193], v[124:127]
	v_mfma_f32_16x16x32_bf16 v[116:119], v[166:169], v[190:193], v[116:119]
	v_mfma_f32_16x16x32_bf16 v[108:111], v[158:161], v[202:205], v[108:111]
	v_mfma_f32_16x16x32_bf16 v[100:103], v[166:169], v[202:205], v[100:103]
	v_mfma_f32_16x16x32_bf16 v[92:95], v[158:161], v[210:213], v[92:95]
	v_mfma_f32_16x16x32_bf16 v[84:87], v[166:169], v[210:213], v[84:87]
	v_mfma_f32_16x16x32_bf16 v[76:79], v[158:161], v[218:221], v[76:79]
	v_mfma_f32_16x16x32_bf16 v[68:71], v[166:169], v[218:221], v[68:71]
	v_mfma_f32_16x16x32_bf16 v[120:123], v[170:173], v[186:189], v[120:123]
	v_mfma_f32_16x16x32_bf16 v[112:115], v[178:181], v[186:189], v[112:115]
	v_mfma_f32_16x16x32_bf16 v[104:107], v[170:173], v[198:201], v[104:107]
	v_mfma_f32_16x16x32_bf16 v[96:99], v[178:181], v[198:201], v[96:99]
	v_mfma_f32_16x16x32_bf16 v[88:91], v[170:173], v[206:209], v[88:91]
	v_mfma_f32_16x16x32_bf16 v[80:83], v[178:181], v[206:209], v[80:83]
	v_mfma_f32_16x16x32_bf16 v[72:75], v[170:173], v[214:217], v[72:75]
	v_mfma_f32_16x16x32_bf16 v[64:67], v[178:181], v[214:217], v[64:67]
	v_mfma_f32_16x16x32_bf16 v[120:123], v[174:177], v[190:193], v[120:123]
	v_mfma_f32_16x16x32_bf16 v[112:115], v[182:185], v[190:193], v[112:115]
	v_mfma_f32_16x16x32_bf16 v[104:107], v[174:177], v[202:205], v[104:107]
	v_mfma_f32_16x16x32_bf16 v[96:99], v[182:185], v[202:205], v[96:99]
	v_mfma_f32_16x16x32_bf16 v[88:91], v[174:177], v[210:213], v[88:91]
	v_mfma_f32_16x16x32_bf16 v[80:83], v[182:185], v[210:213], v[80:83]
	v_mfma_f32_16x16x32_bf16 v[72:75], v[174:177], v[218:221], v[72:75]
	v_mfma_f32_16x16x32_bf16 v[64:67], v[182:185], v[218:221], v[64:67]
	s_barrier
	s_add_i32 s46, s73, s55
	s_mov_b32 m0, s46
	ds_read_b128 v[186:189], v152 offset:49152
	ds_read_b128 v[190:193], v152 offset:50176
	ds_read_b128 v[198:201], v152 offset:51200
	ds_read_b128 v[202:205], v152 offset:52224
	ds_read_b128 v[206:209], v152 offset:53248
	ds_read_b128 v[210:213], v152 offset:54272
	ds_read_b128 v[214:217], v152 offset:55296
	ds_read_b128 v[218:221], v152 offset:56320
	global_load_lds_dwordx4 v132, s[98:99]
	s_add_i32 m0, s46, 0x2000
	s_add_u32 s42, s42, 0x40080
	s_addc_u32 s43, s43, 0
	s_add_i32 s46, s74, s55
	global_load_lds_dwordx4 v128, s[98:99]
	s_mov_b32 m0, s46
	s_nop 0
	global_load_lds_dwordx4 v132, s[42:43]
	s_add_i32 m0, s46, 0x2000
	s_nop 0
	global_load_lds_dwordx4 v128, s[42:43]
	s_mov_b32 m0, s61
	s_nop 0
	global_load_lds_dwordx4 v134, s[100:101]
	s_mov_b32 m0, s62
	s_nop 0
	global_load_lds_dwordx4 v130, s[100:101]
	s_waitcnt vmcnt(8)
	s_waitcnt lgkmcnt(0)
	s_barrier
	v_mfma_f32_16x16x32_bf16 v[60:63], v[154:157], v[186:189], v[60:63]
	v_mfma_f32_16x16x32_bf16 v[52:55], v[162:165], v[186:189], v[52:55]
	v_mfma_f32_16x16x32_bf16 v[44:47], v[154:157], v[198:201], v[44:47]
	v_mfma_f32_16x16x32_bf16 v[36:39], v[162:165], v[198:201], v[36:39]
	v_mfma_f32_16x16x32_bf16 v[28:31], v[154:157], v[206:209], v[28:31]
	v_mfma_f32_16x16x32_bf16 v[20:23], v[162:165], v[206:209], v[20:23]
	v_mfma_f32_16x16x32_bf16 v[12:15], v[154:157], v[214:217], v[12:15]
	v_mfma_f32_16x16x32_bf16 v[4:7], v[162:165], v[214:217], v[4:7]
	v_mfma_f32_16x16x32_bf16 v[60:63], v[158:161], v[190:193], v[60:63]
	v_mfma_f32_16x16x32_bf16 v[52:55], v[166:169], v[190:193], v[52:55]
	v_mfma_f32_16x16x32_bf16 v[44:47], v[158:161], v[202:205], v[44:47]
	v_mfma_f32_16x16x32_bf16 v[36:39], v[166:169], v[202:205], v[36:39]
	v_mfma_f32_16x16x32_bf16 v[28:31], v[158:161], v[210:213], v[28:31]
	v_mfma_f32_16x16x32_bf16 v[20:23], v[166:169], v[210:213], v[20:23]
	v_mfma_f32_16x16x32_bf16 v[12:15], v[158:161], v[218:221], v[12:15]
	v_mfma_f32_16x16x32_bf16 v[4:7], v[166:169], v[218:221], v[4:7]
	v_mfma_f32_16x16x32_bf16 v[56:59], v[170:173], v[186:189], v[56:59]
	v_mfma_f32_16x16x32_bf16 v[48:51], v[178:181], v[186:189], v[48:51]
	v_mfma_f32_16x16x32_bf16 v[40:43], v[170:173], v[198:201], v[40:43]
	v_mfma_f32_16x16x32_bf16 v[32:35], v[178:181], v[198:201], v[32:35]
	v_mfma_f32_16x16x32_bf16 v[24:27], v[170:173], v[206:209], v[24:27]
	v_mfma_f32_16x16x32_bf16 v[16:19], v[178:181], v[206:209], v[16:19]
	v_mfma_f32_16x16x32_bf16 v[8:11], v[170:173], v[214:217], v[8:11]
	v_mfma_f32_16x16x32_bf16 v[0:3], v[178:181], v[214:217], v[0:3]
	v_mfma_f32_16x16x32_bf16 v[56:59], v[174:177], v[190:193], v[56:59]
	v_mfma_f32_16x16x32_bf16 v[48:51], v[182:185], v[190:193], v[48:51]
	v_mfma_f32_16x16x32_bf16 v[40:43], v[174:177], v[202:205], v[40:43]
	v_mfma_f32_16x16x32_bf16 v[32:35], v[182:185], v[202:205], v[32:35]
	v_mfma_f32_16x16x32_bf16 v[24:27], v[174:177], v[210:213], v[24:27]
	v_mfma_f32_16x16x32_bf16 v[16:19], v[182:185], v[210:213], v[16:19]
	v_mfma_f32_16x16x32_bf16 v[8:11], v[174:177], v[218:221], v[8:11]
	v_mfma_f32_16x16x32_bf16 v[0:3], v[182:185], v[218:221], v[0:3]
	s_cmp_eq_u32 s72, 12
	s_cbranch_scc1 .Lxl_0
	s_barrier
	s_add_i32 s72, s72, 2
	s_add_u32 s20, s20, 0x100
	s_addc_u32 s21, s21, 0
	s_add_u32 s70, s70, 0x100
	s_addc_u32 s71, s71, 0
	s_cmp_gt_u32 s72, 13
	s_cbranch_scc0 .LBB0_224
.Lxl_0:
	s_and_b64 vcc, s[4:5], s[0:1]
	s_cbranch_vccnz .Lxs_0
	s_barrier
.Lxs_0:
	s_andn2_b64 vcc, s[10:11], s[4:5]
	s_cbranch_vccz .LBB0_227
	s_barrier

; #define PG8_STAGE(bufoff, gbase, voff) do { _Pragma("unroll") for (int _i = 0; _i < 2; ++_i) \
;         __builtin_amdgcn_global_load_lds((const unsigned*)((const char*)(gbase) + (voff)[_i]), (PG8_LAS unsigned*)(lds + (bufoff) + ldsw + _i * 8192), 16, 0, 0); } while (0)
; #define PG8_LDA(dst, b, h) do { _Pragma("unroll") for (int m = 0; m < 4; ++m) _Pragma("unroll") for (int k = 0; k < 2; ++k) dst[m][k] = *(const PG8_LAS bf16x8*)(lds + PG8_SA(b, h) + aoff + m * 2048 + k * 1024); } while (0)
; #define PG8_LDB(dst, b, h) do { _Pragma("unroll") for (int n = 0; n < 2; ++n) _Pragma("unroll") for (int k = 0; k < 2; ++k) dst[n][k] = *(const PG8_LAS bf16x8*)(lds + PG8_SB(b, h) + boff + n * 2048 + k * 1024); } while (0)
; #define PG8_MMA(ai, bj, At, Bt) do { __builtin_amdgcn_s_setprio(1); _Pragma("unroll") for (int m = 0; m < 4; ++m) _Pragma("unroll") for (int n = 0; n < 2; ++n) _Pragma("unroll") for (int k = 0; k < 2; ++k) \
;         acc[ai][bj][m][n] = __builtin_amdgcn_mfma_f32_16x16x32_bf16(Bt[n][k], At[m][k], acc[ai][bj][m][n], 0, 0, 0); __builtin_amdgcn_s_setprio(0); } while (0)
; #define PG8_WAIT_V(n) asm volatile("s_waitcnt vmcnt(" #n ")" ::: "memory")
; #define PG8_WAIT_L(n) asm volatile("s_waitcnt lgkmcnt(" #n ")" ::: "memory")
; template <class Epi, class Sched, bool ALIGN_EPI = false, bool SP2 = false>
; __device__ __forceinline__ void gemm_phase(PG8_LAS unsigned char* lds, const Gemm g, const Sched& S, const Epi& E) {
;     ...
;             const bool last = (t == nt - 2);
;             const char* a1 = cA + (size_t)(t + 1) * kstep;
;             const char* a2 = last ? nA : cA + (size_t)(t + 2) * kstep; const char* b2 = last ? nB : cB + (size_t)(t + 2) * kstep;
;             const char* a3 = a2 + kstep; const char* b3 = b2 + kstep;
;             if (last && has_next) S.a_ready(nxt);
;             if constexpr (SP2) {
;             PG8_LDB(B0, 0, 0); PG8_LDB(B1, 0, 1); PG8_SCHED; PG8_LDA(At, 0, 0); PG8_STAGE(PG8_SA(1, 1), a1 + hstep, voffA);
;             PG8_WAIT_V(8); PG8_WAIT_L(0); PG8_BAR; PG8_MMA(0, 0, At, B0); PG8_MMA(0, 1, At, B1); PG8_BAR; PG8_SCHED;
;             PG8_LDA(At, 0, 1); PG8_STAGE(PG8_SB(0, 0), b2, voffB); PG8_STAGE(PG8_SB(0, 1), b2 + hstep, voffB); PG8_STAGE(PG8_SA(0, 0), a2, voffA);
;             PG8_WAIT_V(8); PG8_WAIT_L(0); PG8_BAR; PG8_MMA(1, 0, At, B0); PG8_MMA(1, 1, At, B1); PG8_BAR; PG8_SCHED;
.LBB0_414:
	ds_read_b128 v[146:149], v165
	ds_read_b128 v[150:153], v165 offset:1024
	ds_read_b128 v[154:157], v165 offset:2048
	ds_read_b128 v[168:171], v165 offset:3072
	ds_read_b128 v[172:175], v166
	ds_read_b128 v[176:179], v166 offset:1024
	ds_read_b128 v[180:183], v166 offset:2048
	ds_read_b128 v[184:187], v166 offset:3072
	s_add_u32 s52, s20, 0xfffc0080
	s_addc_u32 s53, s21, -1
	s_cmp_eq_u32 s84, 12
	s_cselect_b32 s55, s43, s53
	s_cselect_b32 s54, s78, s52
	s_cselect_b32 s53, s19, s81
	s_cselect_b32 s52, s79, s80
	s_add_i32 m0, s35, 0xc000
	ds_read_b128 v[188:191], v167
	ds_read_b128 v[192:195], v167 offset:1024
	ds_read_b128 v[198:201], v167 offset:2048
	ds_read_b128 v[202:205], v167 offset:3072
	ds_read_b128 v[206:209], v167 offset:4096
	ds_read_b128 v[210:213], v167 offset:5120
	ds_read_b128 v[214:217], v167 offset:6144
	ds_read_b128 v[218:221], v167 offset:7168
	global_load_lds_dwordx4 v138, s[20:21]
	s_add_i32 m0, s35, 0xe000
	s_nop 0
	global_load_lds_dwordx4 v140, s[20:21]
	s_waitcnt vmcnt(8)
	s_waitcnt lgkmcnt(0)
	s_barrier
	v_mfma_f32_16x16x32_bf16 v[124:127], v[146:149], v[188:191], v[124:127]
	v_mfma_f32_16x16x32_bf16 v[120:123], v[154:157], v[188:191], v[120:123]
	v_mfma_f32_16x16x32_bf16 v[108:111], v[146:149], v[198:201], v[108:111]
	v_mfma_f32_16x16x32_bf16 v[104:107], v[154:157], v[198:201], v[104:107]
	v_mfma_f32_16x16x32_bf16 v[92:95], v[146:149], v[206:209], v[92:95]
	v_mfma_f32_16x16x32_bf16 v[88:91], v[154:157], v[206:209], v[88:91]
	v_mfma_f32_16x16x32_bf16 v[76:79], v[146:149], v[214:217], v[76:79]
	v_mfma_f32_16x16x32_bf16 v[72:75], v[154:157], v[214:217], v[72:75]
	v_mfma_f32_16x16x32_bf16 v[124:127], v[150:153], v[192:195], v[124:127]
	v_mfma_f32_16x16x32_bf16 v[120:123], v[168:171], v[192:195], v[120:123]
	v_mfma_f32_16x16x32_bf16 v[108:111], v[150:153], v[202:205], v[108:111]
	v_mfma_f32_16x16x32_bf16 v[104:107], v[168:171], v[202:205], v[104:107]
	v_mfma_f32_16x16x32_bf16 v[92:95], v[150:153], v[210:213], v[92:95]
	v_mfma_f32_16x16x32_bf16 v[88:91], v[168:171], v[210:213], v[88:91]
	v_mfma_f32_16x16x32_bf16 v[76:79], v[150:153], v[218:221], v[76:79]
	v_mfma_f32_16x16x32_bf16 v[72:75], v[168:171], v[218:221], v[72:75]
	v_mfma_f32_16x16x32_bf16 v[116:119], v[172:175], v[188:191], v[116:119]
	v_mfma_f32_16x16x32_bf16 v[112:115], v[180:183], v[188:191], v[112:115]
	v_mfma_f32_16x16x32_bf16 v[100:103], v[172:175], v[198:201], v[100:103]
	v_mfma_f32_16x16x32_bf16 v[96:99], v[180:183], v[198:201], v[96:99]
	v_mfma_f32_16x16x32_bf16 v[84:87], v[172:175], v[206:209], v[84:87]
	v_mfma_f32_16x16x32_bf16 v[80:83], v[180:183], v[206:209], v[80:83]
	v_mfma_f32_16x16x32_bf16 v[68:71], v[172:175], v[214:217], v[68:71]
	v_mfma_f32_16x16x32_bf16 v[64:67], v[180:183], v[214:217], v[64:67]
	v_mfma_f32_16x16x32_bf16 v[116:119], v[176:179], v[192:195], v[116:119]
	v_mfma_f32_16x16x32_bf16 v[112:115], v[184:187], v[192:195], v[112:115]
	v_mfma_f32_16x16x32_bf16 v[100:103], v[176:179], v[202:205], v[100:103]
	v_mfma_f32_16x16x32_bf16 v[96:99], v[184:187], v[202:205], v[96:99]
	v_mfma_f32_16x16x32_bf16 v[84:87], v[176:179], v[210:213], v[84:87]
	v_mfma_f32_16x16x32_bf16 v[80:83], v[184:187], v[210:213], v[80:83]
	v_mfma_f32_16x16x32_bf16 v[68:71], v[176:179], v[218:221], v[68:71]
	v_mfma_f32_16x16x32_bf16 v[64:67], v[184:187], v[218:221], v[64:67]
	s_barrier
	s_add_i32 s85, s72, s63
	s_add_u32 s98, s52, s8
	s_addc_u32 s99, s53, s9
	s_add_u32 s100, s54, s8
	s_addc_u32 s101, s55, s9
	s_mov_b32 m0, s85
	ds_read_b128 v[188:191], v167 offset:16384
	ds_read_b128 v[192:195], v167 offset:17408
	ds_read_b128 v[198:201], v167 offset:18432
	ds_read_b128 v[202:205], v167 offset:19456
	ds_read_b128 v[206:209], v167 offset:20480
	ds_read_b128 v[210:213], v167 offset:21504
	ds_read_b128 v[214:217], v167 offset:22528
	ds_read_b128 v[218:221], v167 offset:23552
	global_load_lds_dwordx4 v132, s[52:53]
	s_add_i32 m0, s85, 0x2000
	s_add_u32 s86, s52, 0x40000
	s_addc_u32 s87, s53, 0
	s_add_i32 s85, s73, s63
	global_load_lds_dwordx4 v128, s[52:53]
	s_mov_b32 m0, s85
	s_nop 0
	global_load_lds_dwordx4 v132, s[86:87]
	s_add_i32 m0, s85, 0x2000
	s_nop 0
	global_load_lds_dwordx4 v128, s[86:87]
	s_mov_b32 m0, s35
	s_nop 0
	global_load_lds_dwordx4 v134, s[54:55]
	s_mov_b32 m0, s65
	s_nop 0
	global_load_lds_dwordx4 v130, s[54:55]
	s_waitcnt vmcnt(8)
	s_waitcnt lgkmcnt(0)
	s_barrier
	v_mfma_f32_16x16x32_bf16 v[60:63], v[146:149], v[188:191], v[60:63]
	v_mfma_f32_16x16x32_bf16 v[56:59], v[154:157], v[188:191], v[56:59]
	v_mfma_f32_16x16x32_bf16 v[44:47], v[146:149], v[198:201], v[44:47]
	v_mfma_f32_16x16x32_bf16 v[40:43], v[154:157], v[198:201], v[40:43]
	v_mfma_f32_16x16x32_bf16 v[28:31], v[146:149], v[206:209], v[28:31]
	v_mfma_f32_16x16x32_bf16 v[24:27], v[154:157], v[206:209], v[24:27]
	v_mfma_f32_16x16x32_bf16 v[12:15], v[146:149], v[214:217], v[12:15]
	v_mfma_f32_16x16x32_bf16 v[8:11], v[154:157], v[214:217], v[8:11]
	v_mfma_f32_16x16x32_bf16 v[60:63], v[150:153], v[192:195], v[60:63]
	v_mfma_f32_16x16x32_bf16 v[56:59], v[168:171], v[192:195], v[56:59]
	v_mfma_f32_16x16x32_bf16 v[44:47], v[150:153], v[202:205], v[44:47]
	v_mfma_f32_16x16x32_bf16 v[40:43], v[168:171], v[202:205], v[40:43]
	v_mfma_f32_16x16x32_bf16 v[28:31], v[150:153], v[210:213], v[28:31]
	v_mfma_f32_16x16x32_bf16 v[24:27], v[168:171], v[210:213], v[24:27]
	v_mfma_f32_16x16x32_bf16 v[12:15], v[150:153], v[218:221], v[12:15]
	v_mfma_f32_16x16x32_bf16 v[8:11], v[168:171], v[218:221], v[8:11]
	v_mfma_f32_16x16x32_bf16 v[52:55], v[172:175], v[188:191], v[52:55]
	v_mfma_f32_16x16x32_bf16 v[48:51], v[180:183], v[188:191], v[48:51]
	v_mfma_f32_16x16x32_bf16 v[36:39], v[172:175], v[198:201], v[36:39]
	v_mfma_f32_16x16x32_bf16 v[32:35], v[180:183], v[198:201], v[32:35]
	v_mfma_f32_16x16x32_bf16 v[20:23], v[172:175], v[206:209], v[20:23]
	v_mfma_f32_16x16x32_bf16 v[16:19], v[180:183], v[206:209], v[16:19]
	v_mfma_f32_16x16x32_bf16 v[4:7], v[172:175], v[214:217], v[4:7]
	v_mfma_f32_16x16x32_bf16 v[0:3], v[180:183], v[214:217], v[0:3]
	v_mfma_f32_16x16x32_bf16 v[52:55], v[176:179], v[192:195], v[52:55]
	v_mfma_f32_16x16x32_bf16 v[48:51], v[184:187], v[192:195], v[48:51]
	v_mfma_f32_16x16x32_bf16 v[36:39], v[176:179], v[202:205], v[36:39]
	v_mfma_f32_16x16x32_bf16 v[32:35], v[184:187], v[202:205], v[32:35]
	v_mfma_f32_16x16x32_bf16 v[20:23], v[176:179], v[210:213], v[20:23]
	v_mfma_f32_16x16x32_bf16 v[16:19], v[184:187], v[210:213], v[16:19]
	v_mfma_f32_16x16x32_bf16 v[4:7], v[176:179], v[218:221], v[4:7]
	v_mfma_f32_16x16x32_bf16 v[0:3], v[184:187], v[218:221], v[0:3]
	s_barrier
; #define PG8_STAGE(bufoff, gbase, voff) do { _Pragma("unroll") for (int _i = 0; _i < 2; ++_i) \
;         __builtin_amdgcn_global_load_lds((const unsigned*)((const char*)(gbase) + (voff)[_i]), (PG8_LAS unsigned*)(lds + (bufoff) + ldsw + _i * 8192), 16, 0, 0); } while (0)
; #define PG8_LDA(dst, b, h) do { _Pragma("unroll") for (int m = 0; m < 4; ++m) _Pragma("unroll") for (int k = 0; k < 2; ++k) dst[m][k] = *(const PG8_LAS bf16x8*)(lds + PG8_SA(b, h) + aoff + m * 2048 + k * 1024); } while (0)
; #define PG8_LDB(dst, b, h) do { _Pragma("unroll") for (int n = 0; n < 2; ++n) _Pragma("unroll") for (int k = 0; k < 2; ++k) dst[n][k] = *(const PG8_LAS bf16x8*)(lds + PG8_SB(b, h) + boff + n * 2048 + k * 1024); } while (0)
; #define PG8_MMA(ai, bj, At, Bt) do { __builtin_amdgcn_s_setprio(1); _Pragma("unroll") for (int m = 0; m < 4; ++m) _Pragma("unroll") for (int n = 0; n < 2; ++n) _Pragma("unroll") for (int k = 0; k < 2; ++k) \
;         acc[ai][bj][m][n] = __builtin_amdgcn_mfma_f32_16x16x32_bf16(Bt[n][k], At[m][k], acc[ai][bj][m][n], 0, 0, 0); __builtin_amdgcn_s_setprio(0); } while (0)
; #define PG8_WAIT_V(n) asm volatile("s_waitcnt vmcnt(" #n ")" ::: "memory")
; #define PG8_WAIT_L(n) asm volatile("s_waitcnt lgkmcnt(" #n ")" ::: "memory")
; #define PG8_BAR __builtin_amdgcn_s_barrier()
; #define PG8_SCHED __builtin_amdgcn_sched_barrier(0)
; template <class Epi, class Sched, bool ALIGN_EPI = false, bool SP2 = false>
; __device__ __forceinline__ void gemm_phase(PG8_LAS unsigned char* lds, const Gemm g, const Sched& S, const Epi& E) {
;     ...
;             PG8_LDB(B0, 1, 0); PG8_LDB(B1, 1, 1); PG8_SCHED; PG8_LDA(At, 1, 0); PG8_STAGE(PG8_SA(0, 1), a2 + hstep, voffA);
;             PG8_WAIT_V(8); PG8_WAIT_L(0); PG8_BAR; PG8_MMA(0, 0, At, B0); PG8_MMA(0, 1, At, B1); PG8_BAR; PG8_SCHED;
;             PG8_LDA(At, 1, 1); PG8_STAGE(PG8_SB(1, 0), b3, voffB); PG8_STAGE(PG8_SB(1, 1), b3 + hstep, voffB); PG8_STAGE(PG8_SA(1, 0), a3, voffA);
;             PG8_WAIT_V(8); PG8_WAIT_L(0); PG8_BAR; PG8_MMA(1, 0, At, B0); PG8_MMA(1, 1, At, B1); PG8_BAR; PG8_SCHED;
	s_add_i32 s85, 0, 0x18000
	v_add_u32_e32 v136, s85, v161
	s_add_i32 s86, 0, 0x1c000
	ds_read_b128 v[146:149], v136
	ds_read_b128 v[150:153], v136 offset:1024
	ds_read_b128 v[154:157], v136 offset:2048
	ds_read_b128 v[168:171], v136 offset:3072
	v_add_u32_e32 v136, s86, v161
	ds_read_b128 v[172:175], v136
	ds_read_b128 v[176:179], v136 offset:1024
	ds_read_b128 v[180:183], v136 offset:2048
	ds_read_b128 v[184:187], v136 offset:3072
	s_add_u32 s54, s54, 0x40000
	s_addc_u32 s55, s55, 0
	s_mov_b32 m0, s66
	ds_read_b128 v[188:191], v167 offset:32768
	ds_read_b128 v[192:195], v167 offset:33792
	ds_read_b128 v[198:201], v167 offset:34816
	ds_read_b128 v[202:205], v167 offset:35840
	ds_read_b128 v[206:209], v167 offset:36864
	ds_read_b128 v[210:213], v167 offset:37888
	ds_read_b128 v[214:217], v167 offset:38912
	ds_read_b128 v[218:221], v167 offset:39936
	global_load_lds_dwordx4 v134, s[54:55]
	s_mov_b32 m0, s67
	s_nop 0
	global_load_lds_dwordx4 v130, s[54:55]
	s_waitcnt vmcnt(8)
	s_waitcnt lgkmcnt(0)
	s_barrier
	v_mfma_f32_16x16x32_bf16 v[124:127], v[146:149], v[188:191], v[124:127]
	v_mfma_f32_16x16x32_bf16 v[120:123], v[154:157], v[188:191], v[120:123]
	v_mfma_f32_16x16x32_bf16 v[108:111], v[146:149], v[198:201], v[108:111]
	v_mfma_f32_16x16x32_bf16 v[104:107], v[154:157], v[198:201], v[104:107]
	v_mfma_f32_16x16x32_bf16 v[92:95], v[146:149], v[206:209], v[92:95]
	v_mfma_f32_16x16x32_bf16 v[88:91], v[154:157], v[206:209], v[88:91]
	v_mfma_f32_16x16x32_bf16 v[76:79], v[146:149], v[214:217], v[76:79]
	v_mfma_f32_16x16x32_bf16 v[72:75], v[154:157], v[214:217], v[72:75]
	v_mfma_f32_16x16x32_bf16 v[124:127], v[150:153], v[192:195], v[124:127]
	v_mfma_f32_16x16x32_bf16 v[120:123], v[168:171], v[192:195], v[120:123]
	v_mfma_f32_16x16x32_bf16 v[108:111], v[150:153], v[202:205], v[108:111]
	v_mfma_f32_16x16x32_bf16 v[104:107], v[168:171], v[202:205], v[104:107]
	v_mfma_f32_16x16x32_bf16 v[92:95], v[150:153], v[210:213], v[92:95]
	v_mfma_f32_16x16x32_bf16 v[88:91], v[168:171], v[210:213], v[88:91]
	v_mfma_f32_16x16x32_bf16 v[76:79], v[150:153], v[218:221], v[76:79]
	v_mfma_f32_16x16x32_bf16 v[72:75], v[168:171], v[218:221], v[72:75]
	v_mfma_f32_16x16x32_bf16 v[116:119], v[172:175], v[188:191], v[116:119]
	v_mfma_f32_16x16x32_bf16 v[112:115], v[180:183], v[188:191], v[112:115]
	v_mfma_f32_16x16x32_bf16 v[100:103], v[172:175], v[198:201], v[100:103]
	v_mfma_f32_16x16x32_bf16 v[96:99], v[180:183], v[198:201], v[96:99]
	v_mfma_f32_16x16x32_bf16 v[84:87], v[172:175], v[206:209], v[84:87]
	v_mfma_f32_16x16x32_bf16 v[80:83], v[180:183], v[206:209], v[80:83]
	v_mfma_f32_16x16x32_bf16 v[68:71], v[172:175], v[214:217], v[68:71]
	v_mfma_f32_16x16x32_bf16 v[64:67], v[180:183], v[214:217], v[64:67]
	v_mfma_f32_16x16x32_bf16 v[116:119], v[176:179], v[192:195], v[116:119]
	v_mfma_f32_16x16x32_bf16 v[112:115], v[184:187], v[192:195], v[112:115]
	v_mfma_f32_16x16x32_bf16 v[100:103], v[176:179], v[202:205], v[100:103]
	v_mfma_f32_16x16x32_bf16 v[96:99], v[184:187], v[202:205], v[96:99]
	v_mfma_f32_16x16x32_bf16 v[84:87], v[176:179], v[210:213], v[84:87]
	v_mfma_f32_16x16x32_bf16 v[80:83], v[184:187], v[210:213], v[80:83]
	v_mfma_f32_16x16x32_bf16 v[68:71], v[176:179], v[218:221], v[68:71]
	v_mfma_f32_16x16x32_bf16 v[64:67], v[184:187], v[218:221], v[64:67]
	s_barrier
	s_add_i32 s54, s85, s63
	s_mov_b32 m0, s54
	ds_read_b128 v[188:191], v167 offset:49152
	ds_read_b128 v[192:195], v167 offset:50176
	ds_read_b128 v[198:201], v167 offset:51200
	ds_read_b128 v[202:205], v167 offset:52224
	ds_read_b128 v[206:209], v167 offset:53248
	ds_read_b128 v[210:213], v167 offset:54272
	ds_read_b128 v[214:217], v167 offset:55296
	ds_read_b128 v[218:221], v167 offset:56320
	global_load_lds_dwordx4 v132, s[98:99]
	s_add_i32 m0, s54, 0x2000
	s_add_u32 s52, s52, 0x40080
	s_addc_u32 s53, s53, 0
	s_add_i32 s54, s86, s63
	global_load_lds_dwordx4 v128, s[98:99]
	s_mov_b32 m0, s54
	s_nop 0
	global_load_lds_dwordx4 v132, s[52:53]
	s_add_i32 m0, s54, 0x2000
	s_nop 0
	global_load_lds_dwordx4 v128, s[52:53]
	s_mov_b32 m0, s69
	s_nop 0
	global_load_lds_dwordx4 v134, s[100:101]
	s_mov_b32 m0, s70
	s_nop 0
	global_load_lds_dwordx4 v130, s[100:101]
	s_waitcnt vmcnt(8)
	s_waitcnt lgkmcnt(0)
	s_barrier
	v_mfma_f32_16x16x32_bf16 v[60:63], v[146:149], v[188:191], v[60:63]
	v_mfma_f32_16x16x32_bf16 v[56:59], v[154:157], v[188:191], v[56:59]
	v_mfma_f32_16x16x32_bf16 v[44:47], v[146:149], v[198:201], v[44:47]
	v_mfma_f32_16x16x32_bf16 v[40:43], v[154:157], v[198:201], v[40:43]
	v_mfma_f32_16x16x32_bf16 v[28:31], v[146:149], v[206:209], v[28:31]
	v_mfma_f32_16x16x32_bf16 v[24:27], v[154:157], v[206:209], v[24:27]
	v_mfma_f32_16x16x32_bf16 v[12:15], v[146:149], v[214:217], v[12:15]
	v_mfma_f32_16x16x32_bf16 v[8:11], v[154:157], v[214:217], v[8:11]
	v_mfma_f32_16x16x32_bf16 v[60:63], v[150:153], v[192:195], v[60:63]
	v_mfma_f32_16x16x32_bf16 v[56:59], v[168:171], v[192:195], v[56:59]
	v_mfma_f32_16x16x32_bf16 v[44:47], v[150:153], v[202:205], v[44:47]
	v_mfma_f32_16x16x32_bf16 v[40:43], v[168:171], v[202:205], v[40:43]
	v_mfma_f32_16x16x32_bf16 v[28:31], v[150:153], v[210:213], v[28:31]
	v_mfma_f32_16x16x32_bf16 v[24:27], v[168:171], v[210:213], v[24:27]
	v_mfma_f32_16x16x32_bf16 v[12:15], v[150:153], v[218:221], v[12:15]
	v_mfma_f32_16x16x32_bf16 v[8:11], v[168:171], v[218:221], v[8:11]
	v_mfma_f32_16x16x32_bf16 v[52:55], v[172:175], v[188:191], v[52:55]
	v_mfma_f32_16x16x32_bf16 v[48:51], v[180:183], v[188:191], v[48:51]
	v_mfma_f32_16x16x32_bf16 v[36:39], v[172:175], v[198:201], v[36:39]
	v_mfma_f32_16x16x32_bf16 v[32:35], v[180:183], v[198:201], v[32:35]
	v_mfma_f32_16x16x32_bf16 v[20:23], v[172:175], v[206:209], v[20:23]
	v_mfma_f32_16x16x32_bf16 v[16:19], v[180:183], v[206:209], v[16:19]
	v_mfma_f32_16x16x32_bf16 v[4:7], v[172:175], v[214:217], v[4:7]
	v_mfma_f32_16x16x32_bf16 v[0:3], v[180:183], v[214:217], v[0:3]
	v_mfma_f32_16x16x32_bf16 v[52:55], v[176:179], v[192:195], v[52:55]
	v_mfma_f32_16x16x32_bf16 v[48:51], v[184:187], v[192:195], v[48:51]
	v_mfma_f32_16x16x32_bf16 v[36:39], v[176:179], v[202:205], v[36:39]
	v_mfma_f32_16x16x32_bf16 v[32:35], v[184:187], v[202:205], v[32:35]
	v_mfma_f32_16x16x32_bf16 v[20:23], v[176:179], v[210:213], v[20:23]
	v_mfma_f32_16x16x32_bf16 v[16:19], v[184:187], v[210:213], v[16:19]
	v_mfma_f32_16x16x32_bf16 v[4:7], v[176:179], v[218:221], v[4:7]
	v_mfma_f32_16x16x32_bf16 v[0:3], v[184:187], v[218:221], v[0:3]
	s_cmp_eq_u32 s84, 12
	s_cbranch_scc1 .Lxl_2
	s_barrier
	s_add_i32 s84, s84, 2
	s_add_u32 s20, s20, 0x100
	s_addc_u32 s21, s21, 0
	s_add_u32 s80, s80, 0x100
	s_addc_u32 s81, s81, 0
	s_cmp_gt_u32 s84, 13
	s_cbranch_scc0 .LBB0_414

; #define PG8_BAR __builtin_amdgcn_s_barrier()
; __device__ __forceinline__ unsigned xb_ld(unsigned* p)              { return __hip_atomic_load(p, __ATOMIC_RELAXED, __HIP_MEMORY_SCOPE_AGENT); }
; __device__ __forceinline__ unsigned xb_add(unsigned* p, unsigned v) { return __hip_atomic_fetch_add(p, v, __ATOMIC_RELAXED, __HIP_MEMORY_SCOPE_AGENT); }
; #define XB_SPIN(cond, bar) do { unsigned _sp = 0; while (cond) { __builtin_amdgcn_s_sleep(1); \
;     if ((++_sp & 255u) == 0u) { if (xb_ld(&(bar)[XB_TMO])) break; if (_sp > XB_SPIN_CAP) { atomicAdd(&(bar)[XB_TMO], 1u); break; } } } } while (0)
; template <class Epi, class Sched, bool ALIGN_EPI = false, bool SP2 = false>
; __device__ __forceinline__ void gemm_phase(PG8_LAS unsigned char* lds, const Gemm g, const Sched& S, const Epi& E) {
;     ...
;         if constexpr (ALIGN_EPI) { if (wr == 0) PG8_BAR; }
;         if constexpr (!Epi::AFTER_DRAIN) { E(acc, cur, wr, wc, fr, fq); S.done(cur); }
; __device__ __forceinline__ void xcd_barrier(const XcdBarrier& b) {
;     ...
;             if (og + 1u == (tg + 1u) * nx) xb_add(&bar[XB_TOPGEN], 1u);
;             else XB_SPIN(xb_ld(&bar[XB_TOPGEN]) == tg, bar);
.Lxs_2:
	v_readlane_b32 s101, v249, 49
	s_nop 3
	s_cmp_eq_u32 s101, 0
	s_cbranch_scc1 .Ldw_done_0
	s_add_u32 s98, s28, 0x183500
	s_addc_u32 s99, s29, 0
	v_mov_b32_e32 v251, 0
	s_mov_b32 s100, 0

; #define PG8_STAGE(bufoff, gbase, voff) do { _Pragma("unroll") for (int _i = 0; _i < 2; ++_i) \
;         __builtin_amdgcn_global_load_lds((const unsigned*)((const char*)(gbase) + (voff)[_i]), (PG8_LAS unsigned*)(lds + (bufoff) + ldsw + _i * 8192), 16, 0, 0); } while (0)
; #define PG8_LDA(dst, b, h) do { _Pragma("unroll") for (int m = 0; m < 4; ++m) _Pragma("unroll") for (int k = 0; k < 2; ++k) dst[m][k] = *(const PG8_LAS bf16x8*)(lds + PG8_SA(b, h) + aoff + m * 2048 + k * 1024); } while (0)
; #define PG8_LDB(dst, b, h) do { _Pragma("unroll") for (int n = 0; n < 2; ++n) _Pragma("unroll") for (int k = 0; k < 2; ++k) dst[n][k] = *(const PG8_LAS bf16x8*)(lds + PG8_SB(b, h) + boff + n * 2048 + k * 1024); } while (0)
; #define PG8_MMA(ai, bj, At, Bt) do { __builtin_amdgcn_s_setprio(1); _Pragma("unroll") for (int m = 0; m < 4; ++m) _Pragma("unroll") for (int n = 0; n < 2; ++n) _Pragma("unroll") for (int k = 0; k < 2; ++k) \
;         acc[ai][bj][m][n] = __builtin_amdgcn_mfma_f32_16x16x32_bf16(Bt[n][k], At[m][k], acc[ai][bj][m][n], 0, 0, 0); __builtin_amdgcn_s_setprio(0); } while (0)
; #define PG8_WAIT_V(n) asm volatile("s_waitcnt vmcnt(" #n ")" ::: "memory")
; #define PG8_WAIT_L(n) asm volatile("s_waitcnt lgkmcnt(" #n ")" ::: "memory")
; template <class Epi, class Sched, bool ALIGN_EPI = false, bool SP2 = false>
; __device__ __forceinline__ void gemm_phase(PG8_LAS unsigned char* lds, const Gemm g, const Sched& S, const Epi& E) {
;     ...
;             const bool last = (t == nt - 2);
;             const char* a1 = cA + (size_t)(t + 1) * kstep;
;             const char* a2 = last ? nA : cA + (size_t)(t + 2) * kstep; const char* b2 = last ? nB : cB + (size_t)(t + 2) * kstep;
;             const char* a3 = a2 + kstep; const char* b3 = b2 + kstep;
;             if (last && has_next) S.a_ready(nxt);
;             if constexpr (SP2) {
;             PG8_LDB(B0, 0, 0); PG8_LDB(B1, 0, 1); PG8_SCHED; PG8_LDA(At, 0, 0); PG8_STAGE(PG8_SA(1, 1), a1 + hstep, voffA);
;             PG8_WAIT_V(8); PG8_WAIT_L(0); PG8_BAR; PG8_MMA(0, 0, At, B0); PG8_MMA(0, 1, At, B1); PG8_BAR; PG8_SCHED;
;             PG8_LDA(At, 0, 1); PG8_STAGE(PG8_SB(0, 0), b2, voffB); PG8_STAGE(PG8_SB(0, 1), b2 + hstep, voffB); PG8_STAGE(PG8_SA(0, 0), a2, voffA);
;             PG8_WAIT_V(8); PG8_WAIT_L(0); PG8_BAR; PG8_MMA(1, 0, At, B0); PG8_MMA(1, 1, At, B1); PG8_BAR; PG8_SCHED;
.LBB0_705:
	ds_read_b128 v[96:99], v223
	ds_read_b128 v[108:111], v223 offset:1024
	ds_read_b128 v[120:123], v223 offset:2048
	ds_read_b128 v[128:131], v223 offset:3072
	ds_read_b128 v[144:147], v224
	ds_read_b128 v[148:151], v224 offset:1024
	ds_read_b128 v[152:155], v224 offset:2048
	ds_read_b128 v[156:159], v224 offset:3072
	s_add_u32 s54, s20, 0xfffc0080
	s_addc_u32 s55, s21, -1
	s_cmp_eq_u32 s76, 12
	s_cselect_b32 s57, s35, s55
	s_cselect_b32 s56, s47, s54
	s_cselect_b32 s55, s45, s75
	s_cselect_b32 s54, s73, s74
	s_add_i32 m0, s53, 0xc000
	ds_read_b128 v[160:163], v225
	ds_read_b128 v[164:167], v225 offset:1024
	ds_read_b128 v[168:171], v225 offset:2048
	ds_read_b128 v[172:175], v225 offset:3072
	ds_read_b128 v[176:179], v225 offset:4096
	ds_read_b128 v[180:183], v225 offset:5120
	ds_read_b128 v[202:205], v225 offset:6144
	ds_read_b128 v[206:209], v225 offset:7168
	global_load_lds_dwordx4 v192, s[20:21]
	s_add_i32 m0, s53, 0xe000
	s_nop 0
	global_load_lds_dwordx4 v194, s[20:21]
	s_waitcnt vmcnt(8)
	s_waitcnt lgkmcnt(0)
	s_barrier
	v_mfma_f32_16x16x32_bf16 v[140:143], v[96:99], v[160:163], v[140:143]
	v_mfma_f32_16x16x32_bf16 v[136:139], v[120:123], v[160:163], v[136:139]
	v_mfma_f32_16x16x32_bf16 v[116:119], v[96:99], v[168:171], v[116:119]
	v_mfma_f32_16x16x32_bf16 v[112:115], v[120:123], v[168:171], v[112:115]
	v_mfma_f32_16x16x32_bf16 v[92:95], v[96:99], v[176:179], v[92:95]
	v_mfma_f32_16x16x32_bf16 v[88:91], v[120:123], v[176:179], v[88:91]
	v_mfma_f32_16x16x32_bf16 v[76:79], v[96:99], v[202:205], v[76:79]
	v_mfma_f32_16x16x32_bf16 v[72:75], v[120:123], v[202:205], v[72:75]
	v_mfma_f32_16x16x32_bf16 v[140:143], v[108:111], v[164:167], v[140:143]
	v_mfma_f32_16x16x32_bf16 v[136:139], v[128:131], v[164:167], v[136:139]
	v_mfma_f32_16x16x32_bf16 v[116:119], v[108:111], v[172:175], v[116:119]
	v_mfma_f32_16x16x32_bf16 v[112:115], v[128:131], v[172:175], v[112:115]
	v_mfma_f32_16x16x32_bf16 v[92:95], v[108:111], v[180:183], v[92:95]
	v_mfma_f32_16x16x32_bf16 v[88:91], v[128:131], v[180:183], v[88:91]
	v_mfma_f32_16x16x32_bf16 v[76:79], v[108:111], v[206:209], v[76:79]
	v_mfma_f32_16x16x32_bf16 v[72:75], v[128:131], v[206:209], v[72:75]
	v_mfma_f32_16x16x32_bf16 v[132:135], v[144:147], v[160:163], v[132:135]
	v_mfma_f32_16x16x32_bf16 v[124:127], v[152:155], v[160:163], v[124:127]
	v_mfma_f32_16x16x32_bf16 v[104:107], v[144:147], v[168:171], v[104:107]
	v_mfma_f32_16x16x32_bf16 v[100:103], v[152:155], v[168:171], v[100:103]
	v_mfma_f32_16x16x32_bf16 v[84:87], v[144:147], v[176:179], v[84:87]
	v_mfma_f32_16x16x32_bf16 v[80:83], v[152:155], v[176:179], v[80:83]
	v_mfma_f32_16x16x32_bf16 v[68:71], v[144:147], v[202:205], v[68:71]
	v_mfma_f32_16x16x32_bf16 v[64:67], v[152:155], v[202:205], v[64:67]
	v_mfma_f32_16x16x32_bf16 v[132:135], v[148:151], v[164:167], v[132:135]
	v_mfma_f32_16x16x32_bf16 v[124:127], v[156:159], v[164:167], v[124:127]
	v_mfma_f32_16x16x32_bf16 v[104:107], v[148:151], v[172:175], v[104:107]
	v_mfma_f32_16x16x32_bf16 v[100:103], v[156:159], v[172:175], v[100:103]
	v_mfma_f32_16x16x32_bf16 v[84:87], v[148:151], v[180:183], v[84:87]
	v_mfma_f32_16x16x32_bf16 v[80:83], v[156:159], v[180:183], v[80:83]
	v_mfma_f32_16x16x32_bf16 v[68:71], v[148:151], v[206:209], v[68:71]
	v_mfma_f32_16x16x32_bf16 v[64:67], v[156:159], v[206:209], v[64:67]
	s_barrier
	s_add_i32 s77, s71, s58
	s_add_u32 s98, s54, s12
	s_addc_u32 s99, s55, s13
	s_add_u32 s100, s56, s12
	s_addc_u32 s101, s57, s13
	s_mov_b32 m0, s77
	ds_read_b128 v[160:163], v225 offset:16384
	ds_read_b128 v[164:167], v225 offset:17408
	ds_read_b128 v[168:171], v225 offset:18432
	ds_read_b128 v[172:175], v225 offset:19456
	ds_read_b128 v[176:179], v225 offset:20480
	ds_read_b128 v[180:183], v225 offset:21504
	ds_read_b128 v[202:205], v225 offset:22528
	ds_read_b128 v[206:209], v225 offset:23552
	global_load_lds_dwordx4 v186, s[54:55]
	s_add_i32 m0, s77, 0x2000
	s_add_u32 s78, s54, 0x40000
	s_addc_u32 s79, s55, 0
	s_add_i32 s77, s72, s58
	global_load_lds_dwordx4 v190, s[54:55]
	s_mov_b32 m0, s77
	s_nop 0
	global_load_lds_dwordx4 v186, s[78:79]
	s_add_i32 m0, s77, 0x2000
	s_nop 0
	global_load_lds_dwordx4 v190, s[78:79]
	s_mov_b32 m0, s53
	s_nop 0
	global_load_lds_dwordx4 v184, s[56:57]
	s_mov_b32 m0, s59
	s_nop 0
	global_load_lds_dwordx4 v188, s[56:57]
	s_waitcnt vmcnt(8)
	s_waitcnt lgkmcnt(0)
	s_barrier
	v_mfma_f32_16x16x32_bf16 v[60:63], v[96:99], v[160:163], v[60:63]
	v_mfma_f32_16x16x32_bf16 v[56:59], v[120:123], v[160:163], v[56:59]
	v_mfma_f32_16x16x32_bf16 v[44:47], v[96:99], v[168:171], v[44:47]
	v_mfma_f32_16x16x32_bf16 v[40:43], v[120:123], v[168:171], v[40:43]
	v_mfma_f32_16x16x32_bf16 v[28:31], v[96:99], v[176:179], v[28:31]
	v_mfma_f32_16x16x32_bf16 v[24:27], v[120:123], v[176:179], v[24:27]
	v_mfma_f32_16x16x32_bf16 v[12:15], v[96:99], v[202:205], v[12:15]
	v_mfma_f32_16x16x32_bf16 v[8:11], v[120:123], v[202:205], v[8:11]
	v_mfma_f32_16x16x32_bf16 v[60:63], v[108:111], v[164:167], v[60:63]
	v_mfma_f32_16x16x32_bf16 v[56:59], v[128:131], v[164:167], v[56:59]
	v_mfma_f32_16x16x32_bf16 v[44:47], v[108:111], v[172:175], v[44:47]
	v_mfma_f32_16x16x32_bf16 v[40:43], v[128:131], v[172:175], v[40:43]
	v_mfma_f32_16x16x32_bf16 v[28:31], v[108:111], v[180:183], v[28:31]
	v_mfma_f32_16x16x32_bf16 v[24:27], v[128:131], v[180:183], v[24:27]
	v_mfma_f32_16x16x32_bf16 v[12:15], v[108:111], v[206:209], v[12:15]
	v_mfma_f32_16x16x32_bf16 v[8:11], v[128:131], v[206:209], v[8:11]
	v_mfma_f32_16x16x32_bf16 v[52:55], v[144:147], v[160:163], v[52:55]
	v_mfma_f32_16x16x32_bf16 v[48:51], v[152:155], v[160:163], v[48:51]
	v_mfma_f32_16x16x32_bf16 v[36:39], v[144:147], v[168:171], v[36:39]
	v_mfma_f32_16x16x32_bf16 v[32:35], v[152:155], v[168:171], v[32:35]
	v_mfma_f32_16x16x32_bf16 v[20:23], v[144:147], v[176:179], v[20:23]
	v_mfma_f32_16x16x32_bf16 v[16:19], v[152:155], v[176:179], v[16:19]
	v_mfma_f32_16x16x32_bf16 v[4:7], v[144:147], v[202:205], v[4:7]
	v_mfma_f32_16x16x32_bf16 v[0:3], v[152:155], v[202:205], v[0:3]
	v_mfma_f32_16x16x32_bf16 v[52:55], v[148:151], v[164:167], v[52:55]
	v_mfma_f32_16x16x32_bf16 v[48:51], v[156:159], v[164:167], v[48:51]
	v_mfma_f32_16x16x32_bf16 v[36:39], v[148:151], v[172:175], v[36:39]
	v_mfma_f32_16x16x32_bf16 v[32:35], v[156:159], v[172:175], v[32:35]
	v_mfma_f32_16x16x32_bf16 v[20:23], v[148:151], v[180:183], v[20:23]
	v_mfma_f32_16x16x32_bf16 v[16:19], v[156:159], v[180:183], v[16:19]
	v_mfma_f32_16x16x32_bf16 v[4:7], v[148:151], v[206:209], v[4:7]
	v_mfma_f32_16x16x32_bf16 v[0:3], v[156:159], v[206:209], v[0:3]
	s_barrier
; #define PG8_STAGE(bufoff, gbase, voff) do { _Pragma("unroll") for (int _i = 0; _i < 2; ++_i) \
;         __builtin_amdgcn_global_load_lds((const unsigned*)((const char*)(gbase) + (voff)[_i]), (PG8_LAS unsigned*)(lds + (bufoff) + ldsw + _i * 8192), 16, 0, 0); } while (0)
; #define PG8_LDA(dst, b, h) do { _Pragma("unroll") for (int m = 0; m < 4; ++m) _Pragma("unroll") for (int k = 0; k < 2; ++k) dst[m][k] = *(const PG8_LAS bf16x8*)(lds + PG8_SA(b, h) + aoff + m * 2048 + k * 1024); } while (0)
; #define PG8_LDB(dst, b, h) do { _Pragma("unroll") for (int n = 0; n < 2; ++n) _Pragma("unroll") for (int k = 0; k < 2; ++k) dst[n][k] = *(const PG8_LAS bf16x8*)(lds + PG8_SB(b, h) + boff + n * 2048 + k * 1024); } while (0)
; #define PG8_MMA(ai, bj, At, Bt) do { __builtin_amdgcn_s_setprio(1); _Pragma("unroll") for (int m = 0; m < 4; ++m) _Pragma("unroll") for (int n = 0; n < 2; ++n) _Pragma("unroll") for (int k = 0; k < 2; ++k) \
;         acc[ai][bj][m][n] = __builtin_amdgcn_mfma_f32_16x16x32_bf16(Bt[n][k], At[m][k], acc[ai][bj][m][n], 0, 0, 0); __builtin_amdgcn_s_setprio(0); } while (0)
; #define PG8_WAIT_V(n) asm volatile("s_waitcnt vmcnt(" #n ")" ::: "memory")
; #define PG8_WAIT_L(n) asm volatile("s_waitcnt lgkmcnt(" #n ")" ::: "memory")
; #define PG8_BAR __builtin_amdgcn_s_barrier()
; #define PG8_SCHED __builtin_amdgcn_sched_barrier(0)
; template <class Epi, class Sched, bool ALIGN_EPI = false, bool SP2 = false>
; __device__ __forceinline__ void gemm_phase(PG8_LAS unsigned char* lds, const Gemm g, const Sched& S, const Epi& E) {
;     ...
;             PG8_LDB(B0, 1, 0); PG8_LDB(B1, 1, 1); PG8_SCHED; PG8_LDA(At, 1, 0); PG8_STAGE(PG8_SA(0, 1), a2 + hstep, voffA);
;             PG8_WAIT_V(8); PG8_WAIT_L(0); PG8_BAR; PG8_MMA(0, 0, At, B0); PG8_MMA(0, 1, At, B1); PG8_BAR; PG8_SCHED;
;             PG8_LDA(At, 1, 1); PG8_STAGE(PG8_SB(1, 0), b3, voffB); PG8_STAGE(PG8_SB(1, 1), b3 + hstep, voffB); PG8_STAGE(PG8_SA(1, 0), a3, voffA);
;             PG8_WAIT_V(8); PG8_WAIT_L(0); PG8_BAR; PG8_MMA(1, 0, At, B0); PG8_MMA(1, 1, At, B1); PG8_BAR; PG8_SCHED;
;     ...
;         if constexpr (ALIGN_EPI) { if (wr == 0) PG8_BAR; }
	s_add_i32 s77, 0, 0x18000
	s_add_i32 s78, 0, 0x1c000
	v_add_u32_e32 v128, s77, v221
	v_add_u32_e32 v156, s78, v221
	ds_read_b128 v[96:99], v128
	ds_read_b128 v[108:111], v128 offset:1024
	ds_read_b128 v[120:123], v128 offset:2048
	ds_read_b128 v[128:131], v128 offset:3072
	ds_read_b128 v[144:147], v156
	ds_read_b128 v[148:151], v156 offset:1024
	ds_read_b128 v[152:155], v156 offset:2048
	ds_read_b128 v[156:159], v156 offset:3072
	s_add_u32 s56, s56, 0x40000
	s_addc_u32 s57, s57, 0
	s_mov_b32 m0, s60
	ds_read_b128 v[160:163], v225 offset:32768
	ds_read_b128 v[164:167], v225 offset:33792
	ds_read_b128 v[168:171], v225 offset:34816
	ds_read_b128 v[172:175], v225 offset:35840
	ds_read_b128 v[176:179], v225 offset:36864
	ds_read_b128 v[180:183], v225 offset:37888
	ds_read_b128 v[202:205], v225 offset:38912
	ds_read_b128 v[206:209], v225 offset:39936
	global_load_lds_dwordx4 v184, s[56:57]
	s_mov_b32 m0, s61
	s_nop 0
	global_load_lds_dwordx4 v188, s[56:57]
	s_waitcnt vmcnt(8)
	s_waitcnt lgkmcnt(0)
	s_barrier
	v_mfma_f32_16x16x32_bf16 v[140:143], v[96:99], v[160:163], v[140:143]
	v_mfma_f32_16x16x32_bf16 v[136:139], v[120:123], v[160:163], v[136:139]
	v_mfma_f32_16x16x32_bf16 v[116:119], v[96:99], v[168:171], v[116:119]
	v_mfma_f32_16x16x32_bf16 v[112:115], v[120:123], v[168:171], v[112:115]
	v_mfma_f32_16x16x32_bf16 v[92:95], v[96:99], v[176:179], v[92:95]
	v_mfma_f32_16x16x32_bf16 v[88:91], v[120:123], v[176:179], v[88:91]
	v_mfma_f32_16x16x32_bf16 v[76:79], v[96:99], v[202:205], v[76:79]
	v_mfma_f32_16x16x32_bf16 v[72:75], v[120:123], v[202:205], v[72:75]
	v_mfma_f32_16x16x32_bf16 v[140:143], v[108:111], v[164:167], v[140:143]
	v_mfma_f32_16x16x32_bf16 v[136:139], v[128:131], v[164:167], v[136:139]
	v_mfma_f32_16x16x32_bf16 v[116:119], v[108:111], v[172:175], v[116:119]
	v_mfma_f32_16x16x32_bf16 v[112:115], v[128:131], v[172:175], v[112:115]
	v_mfma_f32_16x16x32_bf16 v[92:95], v[108:111], v[180:183], v[92:95]
	v_mfma_f32_16x16x32_bf16 v[88:91], v[128:131], v[180:183], v[88:91]
	v_mfma_f32_16x16x32_bf16 v[76:79], v[108:111], v[206:209], v[76:79]
	v_mfma_f32_16x16x32_bf16 v[72:75], v[128:131], v[206:209], v[72:75]
	v_mfma_f32_16x16x32_bf16 v[132:135], v[144:147], v[160:163], v[132:135]
	v_mfma_f32_16x16x32_bf16 v[124:127], v[152:155], v[160:163], v[124:127]
	v_mfma_f32_16x16x32_bf16 v[104:107], v[144:147], v[168:171], v[104:107]
	v_mfma_f32_16x16x32_bf16 v[100:103], v[152:155], v[168:171], v[100:103]
	v_mfma_f32_16x16x32_bf16 v[84:87], v[144:147], v[176:179], v[84:87]
	v_mfma_f32_16x16x32_bf16 v[80:83], v[152:155], v[176:179], v[80:83]
	v_mfma_f32_16x16x32_bf16 v[68:71], v[144:147], v[202:205], v[68:71]
	v_mfma_f32_16x16x32_bf16 v[64:67], v[152:155], v[202:205], v[64:67]
	v_mfma_f32_16x16x32_bf16 v[132:135], v[148:151], v[164:167], v[132:135]
	v_mfma_f32_16x16x32_bf16 v[124:127], v[156:159], v[164:167], v[124:127]
	v_mfma_f32_16x16x32_bf16 v[104:107], v[148:151], v[172:175], v[104:107]
	v_mfma_f32_16x16x32_bf16 v[100:103], v[156:159], v[172:175], v[100:103]
	v_mfma_f32_16x16x32_bf16 v[84:87], v[148:151], v[180:183], v[84:87]
	v_mfma_f32_16x16x32_bf16 v[80:83], v[156:159], v[180:183], v[80:83]
	v_mfma_f32_16x16x32_bf16 v[68:71], v[148:151], v[206:209], v[68:71]
	v_mfma_f32_16x16x32_bf16 v[64:67], v[156:159], v[206:209], v[64:67]
	s_barrier
	s_add_i32 s56, s77, s58
	s_mov_b32 m0, s56
	ds_read_b128 v[160:163], v225 offset:49152
	ds_read_b128 v[164:167], v225 offset:50176
	ds_read_b128 v[168:171], v225 offset:51200
	ds_read_b128 v[172:175], v225 offset:52224
	ds_read_b128 v[176:179], v225 offset:53248
	ds_read_b128 v[180:183], v225 offset:54272
	ds_read_b128 v[202:205], v225 offset:55296
	ds_read_b128 v[206:209], v225 offset:56320
	global_load_lds_dwordx4 v186, s[98:99]
	s_add_i32 m0, s56, 0x2000
	s_add_u32 s54, s54, 0x40080
	s_addc_u32 s55, s55, 0
	s_add_i32 s56, s78, s58
	global_load_lds_dwordx4 v190, s[98:99]
	s_mov_b32 m0, s56
	s_nop 0
	global_load_lds_dwordx4 v186, s[54:55]
	s_add_i32 m0, s56, 0x2000
	s_nop 0
	global_load_lds_dwordx4 v190, s[54:55]
	s_mov_b32 m0, s66
	s_nop 0
	global_load_lds_dwordx4 v184, s[100:101]
	s_mov_b32 m0, s67
	s_nop 0
	global_load_lds_dwordx4 v188, s[100:101]
	s_waitcnt vmcnt(8)
	s_waitcnt lgkmcnt(0)
	s_barrier
	v_mfma_f32_16x16x32_bf16 v[60:63], v[96:99], v[160:163], v[60:63]
	v_mfma_f32_16x16x32_bf16 v[56:59], v[120:123], v[160:163], v[56:59]
	v_mfma_f32_16x16x32_bf16 v[44:47], v[96:99], v[168:171], v[44:47]
	v_mfma_f32_16x16x32_bf16 v[40:43], v[120:123], v[168:171], v[40:43]
	v_mfma_f32_16x16x32_bf16 v[28:31], v[96:99], v[176:179], v[28:31]
	v_mfma_f32_16x16x32_bf16 v[24:27], v[120:123], v[176:179], v[24:27]
	v_mfma_f32_16x16x32_bf16 v[12:15], v[96:99], v[202:205], v[12:15]
	v_mfma_f32_16x16x32_bf16 v[8:11], v[120:123], v[202:205], v[8:11]
	v_mfma_f32_16x16x32_bf16 v[60:63], v[108:111], v[164:167], v[60:63]
	v_mfma_f32_16x16x32_bf16 v[56:59], v[128:131], v[164:167], v[56:59]
	v_mfma_f32_16x16x32_bf16 v[44:47], v[108:111], v[172:175], v[44:47]
	v_mfma_f32_16x16x32_bf16 v[40:43], v[128:131], v[172:175], v[40:43]
	v_mfma_f32_16x16x32_bf16 v[28:31], v[108:111], v[180:183], v[28:31]
	v_mfma_f32_16x16x32_bf16 v[24:27], v[128:131], v[180:183], v[24:27]
	v_mfma_f32_16x16x32_bf16 v[12:15], v[108:111], v[206:209], v[12:15]
	v_mfma_f32_16x16x32_bf16 v[8:11], v[128:131], v[206:209], v[8:11]
	v_mfma_f32_16x16x32_bf16 v[52:55], v[144:147], v[160:163], v[52:55]
	v_mfma_f32_16x16x32_bf16 v[48:51], v[152:155], v[160:163], v[48:51]
	v_mfma_f32_16x16x32_bf16 v[36:39], v[144:147], v[168:171], v[36:39]
	v_mfma_f32_16x16x32_bf16 v[32:35], v[152:155], v[168:171], v[32:35]
	v_mfma_f32_16x16x32_bf16 v[20:23], v[144:147], v[176:179], v[20:23]
	v_mfma_f32_16x16x32_bf16 v[16:19], v[152:155], v[176:179], v[16:19]
	v_mfma_f32_16x16x32_bf16 v[4:7], v[144:147], v[202:205], v[4:7]
	v_mfma_f32_16x16x32_bf16 v[0:3], v[152:155], v[202:205], v[0:3]
	v_mfma_f32_16x16x32_bf16 v[52:55], v[148:151], v[164:167], v[52:55]
	v_mfma_f32_16x16x32_bf16 v[48:51], v[156:159], v[164:167], v[48:51]
	v_mfma_f32_16x16x32_bf16 v[36:39], v[148:151], v[172:175], v[36:39]
	v_mfma_f32_16x16x32_bf16 v[32:35], v[156:159], v[172:175], v[32:35]
	v_mfma_f32_16x16x32_bf16 v[20:23], v[148:151], v[180:183], v[20:23]
	v_mfma_f32_16x16x32_bf16 v[16:19], v[156:159], v[180:183], v[16:19]
	v_mfma_f32_16x16x32_bf16 v[4:7], v[148:151], v[206:209], v[4:7]
	v_mfma_f32_16x16x32_bf16 v[0:3], v[156:159], v[206:209], v[0:3]
	s_cmp_eq_u32 s76, 12
	s_cbranch_scc1 .Lxl_4
	s_barrier
	s_add_i32 s76, s76, 2
	s_add_u32 s20, s20, 0x100
	s_addc_u32 s21, s21, 0
	s_add_u32 s74, s74, 0x100
	s_addc_u32 s75, s75, 0
	s_cmp_gt_u32 s76, 13
	s_cbranch_scc0 .LBB0_705
.Lxl_4:
	s_and_b64 vcc, s[6:7], s[10:11]
	s_cbranch_vccnz .Lxs_4
	s_barrier
.Lxs_4:
	s_andn2_b64 vcc, s[14:15], s[6:7]
	s_cbranch_vccz .LBB0_708
	s_barrier

; #define PG8_STAGE(bufoff, gbase, voff) do { _Pragma("unroll") for (int _i = 0; _i < 2; ++_i) \
;         __builtin_amdgcn_global_load_lds((const unsigned*)((const char*)(gbase) + (voff)[_i]), (PG8_LAS unsigned*)(lds + (bufoff) + ldsw + _i * 8192), 16, 0, 0); } while (0)
; #define PG8_LDA(dst, b, h) do { _Pragma("unroll") for (int m = 0; m < 4; ++m) _Pragma("unroll") for (int k = 0; k < 2; ++k) dst[m][k] = *(const PG8_LAS bf16x8*)(lds + PG8_SA(b, h) + aoff + m * 2048 + k * 1024); } while (0)
; #define PG8_LDB(dst, b, h) do { _Pragma("unroll") for (int n = 0; n < 2; ++n) _Pragma("unroll") for (int k = 0; k < 2; ++k) dst[n][k] = *(const PG8_LAS bf16x8*)(lds + PG8_SB(b, h) + boff + n * 2048 + k * 1024); } while (0)
; #define PG8_MMA(ai, bj, At, Bt) do { __builtin_amdgcn_s_setprio(1); _Pragma("unroll") for (int m = 0; m < 4; ++m) _Pragma("unroll") for (int n = 0; n < 2; ++n) _Pragma("unroll") for (int k = 0; k < 2; ++k) \
;         acc[ai][bj][m][n] = __builtin_amdgcn_mfma_f32_16x16x32_bf16(Bt[n][k], At[m][k], acc[ai][bj][m][n], 0, 0, 0); __builtin_amdgcn_s_setprio(0); } while (0)
; #define PG8_WAIT_V(n) asm volatile("s_waitcnt vmcnt(" #n ")" ::: "memory")
; #define PG8_WAIT_L(n) asm volatile("s_waitcnt lgkmcnt(" #n ")" ::: "memory")
; template <class Epi, class Sched, bool ALIGN_EPI = false, bool SP2 = false>
; __device__ __forceinline__ void gemm_phase(PG8_LAS unsigned char* lds, const Gemm g, const Sched& S, const Epi& E) {
;     ...
;             const bool last = (t == nt - 2);
;             const char* a1 = cA + (size_t)(t + 1) * kstep;
;             const char* a2 = last ? nA : cA + (size_t)(t + 2) * kstep; const char* b2 = last ? nB : cB + (size_t)(t + 2) * kstep;
;             const char* a3 = a2 + kstep; const char* b3 = b2 + kstep;
;             if (last && has_next) S.a_ready(nxt);
;             if constexpr (SP2) {
;             PG8_LDB(B0, 0, 0); PG8_LDB(B1, 0, 1); PG8_SCHED; PG8_LDA(At, 0, 0); PG8_STAGE(PG8_SA(1, 1), a1 + hstep, voffA);
;             PG8_WAIT_V(8); PG8_WAIT_L(0); PG8_BAR; PG8_MMA(0, 0, At, B0); PG8_MMA(0, 1, At, B1); PG8_BAR; PG8_SCHED;
;             PG8_LDA(At, 0, 1); PG8_STAGE(PG8_SB(0, 0), b2, voffB); PG8_STAGE(PG8_SB(0, 1), b2 + hstep, voffB); PG8_STAGE(PG8_SA(0, 0), a2, voffA);
;             PG8_WAIT_V(8); PG8_WAIT_L(0); PG8_BAR; PG8_MMA(1, 0, At, B0); PG8_MMA(1, 1, At, B1); PG8_BAR; PG8_SCHED;
.LBB0_810:
	ds_read_b128 v[154:157], v150
	ds_read_b128 v[158:161], v150 offset:1024
	ds_read_b128 v[162:165], v150 offset:2048
	ds_read_b128 v[166:169], v150 offset:3072
	ds_read_b128 v[170:173], v151
	ds_read_b128 v[174:177], v151 offset:1024
	ds_read_b128 v[178:181], v151 offset:2048
	ds_read_b128 v[182:185], v151 offset:3072
	s_add_u32 s38, s20, 0xfffc0080
	s_addc_u32 s39, s21, -1
	s_cmp_eq_u32 s69, 12
	s_cselect_b32 s45, s15, s39
	s_cselect_b32 s44, s65, s38
	s_cselect_b32 s39, s13, s68
	s_cselect_b32 s38, s66, s67
	s_add_i32 m0, s35, 0xc000
	ds_read_b128 v[186:189], v152
	ds_read_b128 v[190:193], v152 offset:1024
	ds_read_b128 v[198:201], v152 offset:2048
	ds_read_b128 v[202:205], v152 offset:3072
	ds_read_b128 v[206:209], v152 offset:4096
	ds_read_b128 v[210:213], v152 offset:5120
	ds_read_b128 v[214:217], v152 offset:6144
	ds_read_b128 v[218:221], v152 offset:7168
	global_load_lds_dwordx4 v136, s[20:21]
	s_add_i32 m0, s35, 0xe000
	s_nop 0
	global_load_lds_dwordx4 v138, s[20:21]
	s_waitcnt vmcnt(8)
	s_waitcnt lgkmcnt(0)
	s_barrier
	v_mfma_f32_16x16x32_bf16 v[124:127], v[154:157], v[186:189], v[124:127]
	v_mfma_f32_16x16x32_bf16 v[116:119], v[162:165], v[186:189], v[116:119]
	v_mfma_f32_16x16x32_bf16 v[108:111], v[154:157], v[198:201], v[108:111]
	v_mfma_f32_16x16x32_bf16 v[100:103], v[162:165], v[198:201], v[100:103]
	v_mfma_f32_16x16x32_bf16 v[92:95], v[154:157], v[206:209], v[92:95]
	v_mfma_f32_16x16x32_bf16 v[84:87], v[162:165], v[206:209], v[84:87]
	v_mfma_f32_16x16x32_bf16 v[76:79], v[154:157], v[214:217], v[76:79]
	v_mfma_f32_16x16x32_bf16 v[68:71], v[162:165], v[214:217], v[68:71]
	v_mfma_f32_16x16x32_bf16 v[124:127], v[158:161], v[190:193], v[124:127]
	v_mfma_f32_16x16x32_bf16 v[116:119], v[166:169], v[190:193], v[116:119]
	v_mfma_f32_16x16x32_bf16 v[108:111], v[158:161], v[202:205], v[108:111]
	v_mfma_f32_16x16x32_bf16 v[100:103], v[166:169], v[202:205], v[100:103]
	v_mfma_f32_16x16x32_bf16 v[92:95], v[158:161], v[210:213], v[92:95]
	v_mfma_f32_16x16x32_bf16 v[84:87], v[166:169], v[210:213], v[84:87]
	v_mfma_f32_16x16x32_bf16 v[76:79], v[158:161], v[218:221], v[76:79]
	v_mfma_f32_16x16x32_bf16 v[68:71], v[166:169], v[218:221], v[68:71]
	v_mfma_f32_16x16x32_bf16 v[120:123], v[170:173], v[186:189], v[120:123]
	v_mfma_f32_16x16x32_bf16 v[112:115], v[178:181], v[186:189], v[112:115]
	v_mfma_f32_16x16x32_bf16 v[104:107], v[170:173], v[198:201], v[104:107]
	v_mfma_f32_16x16x32_bf16 v[96:99], v[178:181], v[198:201], v[96:99]
	v_mfma_f32_16x16x32_bf16 v[88:91], v[170:173], v[206:209], v[88:91]
	v_mfma_f32_16x16x32_bf16 v[80:83], v[178:181], v[206:209], v[80:83]
	v_mfma_f32_16x16x32_bf16 v[72:75], v[170:173], v[214:217], v[72:75]
	v_mfma_f32_16x16x32_bf16 v[64:67], v[178:181], v[214:217], v[64:67]
	v_mfma_f32_16x16x32_bf16 v[120:123], v[174:177], v[190:193], v[120:123]
	v_mfma_f32_16x16x32_bf16 v[112:115], v[182:185], v[190:193], v[112:115]
	v_mfma_f32_16x16x32_bf16 v[104:107], v[174:177], v[202:205], v[104:107]
	v_mfma_f32_16x16x32_bf16 v[96:99], v[182:185], v[202:205], v[96:99]
	v_mfma_f32_16x16x32_bf16 v[88:91], v[174:177], v[210:213], v[88:91]
	v_mfma_f32_16x16x32_bf16 v[80:83], v[182:185], v[210:213], v[80:83]
	v_mfma_f32_16x16x32_bf16 v[72:75], v[174:177], v[218:221], v[72:75]
	v_mfma_f32_16x16x32_bf16 v[64:67], v[182:185], v[218:221], v[64:67]
	s_barrier
	s_add_i32 s70, s60, s52
	s_add_u32 s98, s38, s8
	s_addc_u32 s99, s39, s9
	s_add_u32 s100, s44, s8
	s_addc_u32 s101, s45, s9
	s_mov_b32 m0, s70
	ds_read_b128 v[186:189], v152 offset:16384
	ds_read_b128 v[190:193], v152 offset:17408
	ds_read_b128 v[198:201], v152 offset:18432
	ds_read_b128 v[202:205], v152 offset:19456
	ds_read_b128 v[206:209], v152 offset:20480
	ds_read_b128 v[210:213], v152 offset:21504
	ds_read_b128 v[214:217], v152 offset:22528
	ds_read_b128 v[218:221], v152 offset:23552
	global_load_lds_dwordx4 v132, s[38:39]
	s_add_i32 m0, s70, 0x2000
	s_add_u32 s70, s38, 0x40000
	s_addc_u32 s71, s39, 0
	s_add_i32 s72, s61, s52
	global_load_lds_dwordx4 v128, s[38:39]
	s_mov_b32 m0, s72
	s_nop 0
	global_load_lds_dwordx4 v132, s[70:71]
	s_add_i32 m0, s72, 0x2000
	s_nop 0
	global_load_lds_dwordx4 v128, s[70:71]
	s_mov_b32 m0, s35
	s_nop 0
	global_load_lds_dwordx4 v134, s[44:45]
	s_mov_b32 m0, s54
	s_nop 0
	global_load_lds_dwordx4 v130, s[44:45]
	s_waitcnt vmcnt(8)
	s_waitcnt lgkmcnt(0)
	s_barrier
	v_mfma_f32_16x16x32_bf16 v[60:63], v[154:157], v[186:189], v[60:63]
	v_mfma_f32_16x16x32_bf16 v[52:55], v[162:165], v[186:189], v[52:55]
	v_mfma_f32_16x16x32_bf16 v[44:47], v[154:157], v[198:201], v[44:47]
	v_mfma_f32_16x16x32_bf16 v[36:39], v[162:165], v[198:201], v[36:39]
	v_mfma_f32_16x16x32_bf16 v[28:31], v[154:157], v[206:209], v[28:31]
	v_mfma_f32_16x16x32_bf16 v[20:23], v[162:165], v[206:209], v[20:23]
	v_mfma_f32_16x16x32_bf16 v[12:15], v[154:157], v[214:217], v[12:15]
	v_mfma_f32_16x16x32_bf16 v[4:7], v[162:165], v[214:217], v[4:7]
	v_mfma_f32_16x16x32_bf16 v[60:63], v[158:161], v[190:193], v[60:63]
	v_mfma_f32_16x16x32_bf16 v[52:55], v[166:169], v[190:193], v[52:55]
	v_mfma_f32_16x16x32_bf16 v[44:47], v[158:161], v[202:205], v[44:47]
	v_mfma_f32_16x16x32_bf16 v[36:39], v[166:169], v[202:205], v[36:39]
	v_mfma_f32_16x16x32_bf16 v[28:31], v[158:161], v[210:213], v[28:31]
	v_mfma_f32_16x16x32_bf16 v[20:23], v[166:169], v[210:213], v[20:23]
	v_mfma_f32_16x16x32_bf16 v[12:15], v[158:161], v[218:221], v[12:15]
	v_mfma_f32_16x16x32_bf16 v[4:7], v[166:169], v[218:221], v[4:7]
	v_mfma_f32_16x16x32_bf16 v[56:59], v[170:173], v[186:189], v[56:59]
	v_mfma_f32_16x16x32_bf16 v[48:51], v[178:181], v[186:189], v[48:51]
	v_mfma_f32_16x16x32_bf16 v[40:43], v[170:173], v[198:201], v[40:43]
	v_mfma_f32_16x16x32_bf16 v[32:35], v[178:181], v[198:201], v[32:35]
	v_mfma_f32_16x16x32_bf16 v[24:27], v[170:173], v[206:209], v[24:27]
	v_mfma_f32_16x16x32_bf16 v[16:19], v[178:181], v[206:209], v[16:19]
	v_mfma_f32_16x16x32_bf16 v[8:11], v[170:173], v[214:217], v[8:11]
	v_mfma_f32_16x16x32_bf16 v[0:3], v[178:181], v[214:217], v[0:3]
	v_mfma_f32_16x16x32_bf16 v[56:59], v[174:177], v[190:193], v[56:59]
	v_mfma_f32_16x16x32_bf16 v[48:51], v[182:185], v[190:193], v[48:51]
	v_mfma_f32_16x16x32_bf16 v[40:43], v[174:177], v[202:205], v[40:43]
	v_mfma_f32_16x16x32_bf16 v[32:35], v[182:185], v[202:205], v[32:35]
	v_mfma_f32_16x16x32_bf16 v[24:27], v[174:177], v[210:213], v[24:27]
	v_mfma_f32_16x16x32_bf16 v[16:19], v[182:185], v[210:213], v[16:19]
	v_mfma_f32_16x16x32_bf16 v[8:11], v[174:177], v[218:221], v[8:11]
	v_mfma_f32_16x16x32_bf16 v[0:3], v[182:185], v[218:221], v[0:3]
	s_barrier
; #define PG8_STAGE(bufoff, gbase, voff) do { _Pragma("unroll") for (int _i = 0; _i < 2; ++_i) \
;         __builtin_amdgcn_global_load_lds((const unsigned*)((const char*)(gbase) + (voff)[_i]), (PG8_LAS unsigned*)(lds + (bufoff) + ldsw + _i * 8192), 16, 0, 0); } while (0)
; #define PG8_LDA(dst, b, h) do { _Pragma("unroll") for (int m = 0; m < 4; ++m) _Pragma("unroll") for (int k = 0; k < 2; ++k) dst[m][k] = *(const PG8_LAS bf16x8*)(lds + PG8_SA(b, h) + aoff + m * 2048 + k * 1024); } while (0)
; #define PG8_LDB(dst, b, h) do { _Pragma("unroll") for (int n = 0; n < 2; ++n) _Pragma("unroll") for (int k = 0; k < 2; ++k) dst[n][k] = *(const PG8_LAS bf16x8*)(lds + PG8_SB(b, h) + boff + n * 2048 + k * 1024); } while (0)
; #define PG8_MMA(ai, bj, At, Bt) do { __builtin_amdgcn_s_setprio(1); _Pragma("unroll") for (int m = 0; m < 4; ++m) _Pragma("unroll") for (int n = 0; n < 2; ++n) _Pragma("unroll") for (int k = 0; k < 2; ++k) \
;         acc[ai][bj][m][n] = __builtin_amdgcn_mfma_f32_16x16x32_bf16(Bt[n][k], At[m][k], acc[ai][bj][m][n], 0, 0, 0); __builtin_amdgcn_s_setprio(0); } while (0)
; #define PG8_WAIT_V(n) asm volatile("s_waitcnt vmcnt(" #n ")" ::: "memory")
; #define PG8_WAIT_L(n) asm volatile("s_waitcnt lgkmcnt(" #n ")" ::: "memory")
; #define PG8_BAR __builtin_amdgcn_s_barrier()
; #define PG8_SCHED __builtin_amdgcn_sched_barrier(0)
; template <class Epi, class Sched, bool ALIGN_EPI = false, bool SP2 = false>
; __device__ __forceinline__ void gemm_phase(PG8_LAS unsigned char* lds, const Gemm g, const Sched& S, const Epi& E) {
;     ...
;             PG8_LDB(B0, 1, 0); PG8_LDB(B1, 1, 1); PG8_SCHED; PG8_LDA(At, 1, 0); PG8_STAGE(PG8_SA(0, 1), a2 + hstep, voffA);
;             PG8_WAIT_V(8); PG8_WAIT_L(0); PG8_BAR; PG8_MMA(0, 0, At, B0); PG8_MMA(0, 1, At, B1); PG8_BAR; PG8_SCHED;
;             PG8_LDA(At, 1, 1); PG8_STAGE(PG8_SB(1, 0), b3, voffB); PG8_STAGE(PG8_SB(1, 1), b3 + hstep, voffB); PG8_STAGE(PG8_SA(1, 0), a3, voffA);
;             PG8_WAIT_V(8); PG8_WAIT_L(0); PG8_BAR; PG8_MMA(1, 0, At, B0); PG8_MMA(1, 1, At, B1); PG8_BAR; PG8_SCHED;
	s_add_i32 s70, 0, 0x18000
	v_add_u32_e32 v153, s70, v147
	s_add_i32 s71, 0, 0x1c000
	ds_read_b128 v[154:157], v153
	ds_read_b128 v[158:161], v153 offset:1024
	ds_read_b128 v[162:165], v153 offset:2048
	ds_read_b128 v[166:169], v153 offset:3072
	v_add_u32_e32 v153, s71, v147
	ds_read_b128 v[170:173], v153
	ds_read_b128 v[174:177], v153 offset:1024
	ds_read_b128 v[178:181], v153 offset:2048
	ds_read_b128 v[182:185], v153 offset:3072
	s_add_u32 s44, s44, 0x40000
	s_addc_u32 s45, s45, 0
	s_mov_b32 m0, s55
	ds_read_b128 v[186:189], v152 offset:32768
	ds_read_b128 v[190:193], v152 offset:33792
	ds_read_b128 v[198:201], v152 offset:34816
	ds_read_b128 v[202:205], v152 offset:35840
	ds_read_b128 v[206:209], v152 offset:36864
	ds_read_b128 v[210:213], v152 offset:37888
	ds_read_b128 v[214:217], v152 offset:38912
	ds_read_b128 v[218:221], v152 offset:39936
	global_load_lds_dwordx4 v134, s[44:45]
	s_mov_b32 m0, s56
	s_nop 0
	global_load_lds_dwordx4 v130, s[44:45]
	s_waitcnt vmcnt(8)
	s_waitcnt lgkmcnt(0)
	s_barrier
	v_mfma_f32_16x16x32_bf16 v[124:127], v[154:157], v[186:189], v[124:127]
	v_mfma_f32_16x16x32_bf16 v[116:119], v[162:165], v[186:189], v[116:119]
	v_mfma_f32_16x16x32_bf16 v[108:111], v[154:157], v[198:201], v[108:111]
	v_mfma_f32_16x16x32_bf16 v[100:103], v[162:165], v[198:201], v[100:103]
	v_mfma_f32_16x16x32_bf16 v[92:95], v[154:157], v[206:209], v[92:95]
	v_mfma_f32_16x16x32_bf16 v[84:87], v[162:165], v[206:209], v[84:87]
	v_mfma_f32_16x16x32_bf16 v[76:79], v[154:157], v[214:217], v[76:79]
	v_mfma_f32_16x16x32_bf16 v[68:71], v[162:165], v[214:217], v[68:71]
	v_mfma_f32_16x16x32_bf16 v[124:127], v[158:161], v[190:193], v[124:127]
	v_mfma_f32_16x16x32_bf16 v[116:119], v[166:169], v[190:193], v[116:119]
	v_mfma_f32_16x16x32_bf16 v[108:111], v[158:161], v[202:205], v[108:111]
	v_mfma_f32_16x16x32_bf16 v[100:103], v[166:169], v[202:205], v[100:103]
	v_mfma_f32_16x16x32_bf16 v[92:95], v[158:161], v[210:213], v[92:95]
	v_mfma_f32_16x16x32_bf16 v[84:87], v[166:169], v[210:213], v[84:87]
	v_mfma_f32_16x16x32_bf16 v[76:79], v[158:161], v[218:221], v[76:79]
	v_mfma_f32_16x16x32_bf16 v[68:71], v[166:169], v[218:221], v[68:71]
	v_mfma_f32_16x16x32_bf16 v[120:123], v[170:173], v[186:189], v[120:123]
	v_mfma_f32_16x16x32_bf16 v[112:115], v[178:181], v[186:189], v[112:115]
	v_mfma_f32_16x16x32_bf16 v[104:107], v[170:173], v[198:201], v[104:107]
	v_mfma_f32_16x16x32_bf16 v[96:99], v[178:181], v[198:201], v[96:99]
	v_mfma_f32_16x16x32_bf16 v[88:91], v[170:173], v[206:209], v[88:91]
	v_mfma_f32_16x16x32_bf16 v[80:83], v[178:181], v[206:209], v[80:83]
	v_mfma_f32_16x16x32_bf16 v[72:75], v[170:173], v[214:217], v[72:75]
	v_mfma_f32_16x16x32_bf16 v[64:67], v[178:181], v[214:217], v[64:67]
	v_mfma_f32_16x16x32_bf16 v[120:123], v[174:177], v[190:193], v[120:123]
	v_mfma_f32_16x16x32_bf16 v[112:115], v[182:185], v[190:193], v[112:115]
	v_mfma_f32_16x16x32_bf16 v[104:107], v[174:177], v[202:205], v[104:107]
	v_mfma_f32_16x16x32_bf16 v[96:99], v[182:185], v[202:205], v[96:99]
	v_mfma_f32_16x16x32_bf16 v[88:91], v[174:177], v[210:213], v[88:91]
	v_mfma_f32_16x16x32_bf16 v[80:83], v[182:185], v[210:213], v[80:83]
	v_mfma_f32_16x16x32_bf16 v[72:75], v[174:177], v[218:221], v[72:75]
	v_mfma_f32_16x16x32_bf16 v[64:67], v[182:185], v[218:221], v[64:67]
	s_barrier
	s_add_i32 s44, s70, s52
	s_mov_b32 m0, s44
	ds_read_b128 v[186:189], v152 offset:49152
	ds_read_b128 v[190:193], v152 offset:50176
	ds_read_b128 v[198:201], v152 offset:51200
	ds_read_b128 v[202:205], v152 offset:52224
	ds_read_b128 v[206:209], v152 offset:53248
	ds_read_b128 v[210:213], v152 offset:54272
	ds_read_b128 v[214:217], v152 offset:55296
	ds_read_b128 v[218:221], v152 offset:56320
	global_load_lds_dwordx4 v132, s[98:99]
	s_add_i32 m0, s44, 0x2000
	s_add_u32 s38, s38, 0x40080
	s_addc_u32 s39, s39, 0
	s_add_i32 s44, s71, s52
	global_load_lds_dwordx4 v128, s[98:99]
	s_mov_b32 m0, s44
	s_nop 0
	global_load_lds_dwordx4 v132, s[38:39]
	s_add_i32 m0, s44, 0x2000
	s_nop 0
	global_load_lds_dwordx4 v128, s[38:39]
	s_mov_b32 m0, s58
	s_nop 0
	global_load_lds_dwordx4 v134, s[100:101]
	s_mov_b32 m0, s59
	s_nop 0
	global_load_lds_dwordx4 v130, s[100:101]
	s_waitcnt vmcnt(8)
	s_waitcnt lgkmcnt(0)
	s_barrier
	v_mfma_f32_16x16x32_bf16 v[60:63], v[154:157], v[186:189], v[60:63]
	v_mfma_f32_16x16x32_bf16 v[52:55], v[162:165], v[186:189], v[52:55]
	v_mfma_f32_16x16x32_bf16 v[44:47], v[154:157], v[198:201], v[44:47]
	v_mfma_f32_16x16x32_bf16 v[36:39], v[162:165], v[198:201], v[36:39]
	v_mfma_f32_16x16x32_bf16 v[28:31], v[154:157], v[206:209], v[28:31]
	v_mfma_f32_16x16x32_bf16 v[20:23], v[162:165], v[206:209], v[20:23]
	v_mfma_f32_16x16x32_bf16 v[12:15], v[154:157], v[214:217], v[12:15]
	v_mfma_f32_16x16x32_bf16 v[4:7], v[162:165], v[214:217], v[4:7]
	v_mfma_f32_16x16x32_bf16 v[60:63], v[158:161], v[190:193], v[60:63]
	v_mfma_f32_16x16x32_bf16 v[52:55], v[166:169], v[190:193], v[52:55]
	v_mfma_f32_16x16x32_bf16 v[44:47], v[158:161], v[202:205], v[44:47]
	v_mfma_f32_16x16x32_bf16 v[36:39], v[166:169], v[202:205], v[36:39]
	v_mfma_f32_16x16x32_bf16 v[28:31], v[158:161], v[210:213], v[28:31]
	v_mfma_f32_16x16x32_bf16 v[20:23], v[166:169], v[210:213], v[20:23]
	v_mfma_f32_16x16x32_bf16 v[12:15], v[158:161], v[218:221], v[12:15]
	v_mfma_f32_16x16x32_bf16 v[4:7], v[166:169], v[218:221], v[4:7]
	v_mfma_f32_16x16x32_bf16 v[56:59], v[170:173], v[186:189], v[56:59]
	v_mfma_f32_16x16x32_bf16 v[48:51], v[178:181], v[186:189], v[48:51]
	v_mfma_f32_16x16x32_bf16 v[40:43], v[170:173], v[198:201], v[40:43]
	v_mfma_f32_16x16x32_bf16 v[32:35], v[178:181], v[198:201], v[32:35]
	v_mfma_f32_16x16x32_bf16 v[24:27], v[170:173], v[206:209], v[24:27]
	v_mfma_f32_16x16x32_bf16 v[16:19], v[178:181], v[206:209], v[16:19]
	v_mfma_f32_16x16x32_bf16 v[8:11], v[170:173], v[214:217], v[8:11]
	v_mfma_f32_16x16x32_bf16 v[0:3], v[178:181], v[214:217], v[0:3]
	v_mfma_f32_16x16x32_bf16 v[56:59], v[174:177], v[190:193], v[56:59]
	v_mfma_f32_16x16x32_bf16 v[48:51], v[182:185], v[190:193], v[48:51]
	v_mfma_f32_16x16x32_bf16 v[40:43], v[174:177], v[202:205], v[40:43]
	v_mfma_f32_16x16x32_bf16 v[32:35], v[182:185], v[202:205], v[32:35]
	v_mfma_f32_16x16x32_bf16 v[24:27], v[174:177], v[210:213], v[24:27]
	v_mfma_f32_16x16x32_bf16 v[16:19], v[182:185], v[210:213], v[16:19]
	v_mfma_f32_16x16x32_bf16 v[8:11], v[174:177], v[218:221], v[8:11]
	v_mfma_f32_16x16x32_bf16 v[0:3], v[182:185], v[218:221], v[0:3]
	s_cmp_eq_u32 s69, 12
	s_cbranch_scc1 .Lxl_5
	s_barrier
	s_add_i32 s69, s69, 2
	s_add_u32 s20, s20, 0x100
	s_addc_u32 s21, s21, 0
	s_add_u32 s67, s67, 0x100
	s_addc_u32 s68, s68, 0
	s_cmp_gt_u32 s69, 13
	s_cbranch_scc0 .LBB0_810

; #define PG8_STAGE(bufoff, gbase, voff) do { _Pragma("unroll") for (int _i = 0; _i < 2; ++_i) \
;         __builtin_amdgcn_global_load_lds((const unsigned*)((const char*)(gbase) + (voff)[_i]), (PG8_LAS unsigned*)(lds + (bufoff) + ldsw + _i * 8192), 16, 0, 0); } while (0)
; #define PG8_LDA(dst, b, h) do { _Pragma("unroll") for (int m = 0; m < 4; ++m) _Pragma("unroll") for (int k = 0; k < 2; ++k) dst[m][k] = *(const PG8_LAS bf16x8*)(lds + PG8_SA(b, h) + aoff + m * 2048 + k * 1024); } while (0)
; #define PG8_LDB(dst, b, h) do { _Pragma("unroll") for (int n = 0; n < 2; ++n) _Pragma("unroll") for (int k = 0; k < 2; ++k) dst[n][k] = *(const PG8_LAS bf16x8*)(lds + PG8_SB(b, h) + boff + n * 2048 + k * 1024); } while (0)
; #define PG8_MMA(ai, bj, At, Bt) do { __builtin_amdgcn_s_setprio(1); _Pragma("unroll") for (int m = 0; m < 4; ++m) _Pragma("unroll") for (int n = 0; n < 2; ++n) _Pragma("unroll") for (int k = 0; k < 2; ++k) \
;         acc[ai][bj][m][n] = __builtin_amdgcn_mfma_f32_16x16x32_bf16(Bt[n][k], At[m][k], acc[ai][bj][m][n], 0, 0, 0); __builtin_amdgcn_s_setprio(0); } while (0)
; #define PG8_WAIT_V(n) asm volatile("s_waitcnt vmcnt(" #n ")" ::: "memory")
; #define PG8_WAIT_L(n) asm volatile("s_waitcnt lgkmcnt(" #n ")" ::: "memory")
; template <class Epi, class Sched, bool ALIGN_EPI = false, bool SP2 = false>
; __device__ __forceinline__ void gemm_phase(PG8_LAS unsigned char* lds, const Gemm g, const Sched& S, const Epi& E) {
;     ...
;             const bool last = (t == nt - 2);
;             const char* a1 = cA + (size_t)(t + 1) * kstep;
;             const char* a2 = last ? nA : cA + (size_t)(t + 2) * kstep; const char* b2 = last ? nB : cB + (size_t)(t + 2) * kstep;
;             const char* a3 = a2 + kstep; const char* b3 = b2 + kstep;
;             if (last && has_next) S.a_ready(nxt);
;             if constexpr (SP2) {
;             PG8_LDB(B0, 0, 0); PG8_LDB(B1, 0, 1); PG8_SCHED; PG8_LDA(At, 0, 0); PG8_STAGE(PG8_SA(1, 1), a1 + hstep, voffA);
;             PG8_WAIT_V(8); PG8_WAIT_L(0); PG8_BAR; PG8_MMA(0, 0, At, B0); PG8_MMA(0, 1, At, B1); PG8_BAR; PG8_SCHED;
;             PG8_LDA(At, 0, 1); PG8_STAGE(PG8_SB(0, 0), b2, voffB); PG8_STAGE(PG8_SB(0, 1), b2 + hstep, voffB); PG8_STAGE(PG8_SA(0, 0), a2, voffA);
;             PG8_WAIT_V(8); PG8_WAIT_L(0); PG8_BAR; PG8_MMA(1, 0, At, B0); PG8_MMA(1, 1, At, B1); PG8_BAR; PG8_SCHED;
.LBB0_1740:
	ds_read_b128 v[154:157], v150
	ds_read_b128 v[158:161], v150 offset:1024
	ds_read_b128 v[162:165], v150 offset:2048
	ds_read_b128 v[166:169], v150 offset:3072
	ds_read_b128 v[170:173], v151
	ds_read_b128 v[174:177], v151 offset:1024
	ds_read_b128 v[178:181], v151 offset:2048
	ds_read_b128 v[182:185], v151 offset:3072
	s_add_u32 s38, s20, 0xfffc0080
	s_addc_u32 s39, s21, -1
	s_cmp_eq_u32 s67, 12
	s_cselect_b32 s43, s15, s39
	s_cselect_b32 s42, s63, s38
	s_cselect_b32 s39, s13, s66
	s_cselect_b32 s38, s64, s65
	s_add_i32 m0, s35, 0xc000
	ds_read_b128 v[186:189], v152
	ds_read_b128 v[190:193], v152 offset:1024
	ds_read_b128 v[198:201], v152 offset:2048
	ds_read_b128 v[202:205], v152 offset:3072
	ds_read_b128 v[206:209], v152 offset:4096
	ds_read_b128 v[210:213], v152 offset:5120
	ds_read_b128 v[214:217], v152 offset:6144
	ds_read_b128 v[218:221], v152 offset:7168
	global_load_lds_dwordx4 v136, s[20:21]
	s_add_i32 m0, s35, 0xe000
	s_nop 0
	global_load_lds_dwordx4 v138, s[20:21]
	s_waitcnt vmcnt(8)
	s_waitcnt lgkmcnt(0)
	s_barrier
	v_mfma_f32_16x16x32_bf16 v[124:127], v[154:157], v[186:189], v[124:127]
	v_mfma_f32_16x16x32_bf16 v[116:119], v[162:165], v[186:189], v[116:119]
	v_mfma_f32_16x16x32_bf16 v[108:111], v[154:157], v[198:201], v[108:111]
	v_mfma_f32_16x16x32_bf16 v[100:103], v[162:165], v[198:201], v[100:103]
	v_mfma_f32_16x16x32_bf16 v[92:95], v[154:157], v[206:209], v[92:95]
	v_mfma_f32_16x16x32_bf16 v[84:87], v[162:165], v[206:209], v[84:87]
	v_mfma_f32_16x16x32_bf16 v[76:79], v[154:157], v[214:217], v[76:79]
	v_mfma_f32_16x16x32_bf16 v[68:71], v[162:165], v[214:217], v[68:71]
	v_mfma_f32_16x16x32_bf16 v[124:127], v[158:161], v[190:193], v[124:127]
	v_mfma_f32_16x16x32_bf16 v[116:119], v[166:169], v[190:193], v[116:119]
	v_mfma_f32_16x16x32_bf16 v[108:111], v[158:161], v[202:205], v[108:111]
	v_mfma_f32_16x16x32_bf16 v[100:103], v[166:169], v[202:205], v[100:103]
	v_mfma_f32_16x16x32_bf16 v[92:95], v[158:161], v[210:213], v[92:95]
	v_mfma_f32_16x16x32_bf16 v[84:87], v[166:169], v[210:213], v[84:87]
	v_mfma_f32_16x16x32_bf16 v[76:79], v[158:161], v[218:221], v[76:79]
	v_mfma_f32_16x16x32_bf16 v[68:71], v[166:169], v[218:221], v[68:71]
	v_mfma_f32_16x16x32_bf16 v[120:123], v[170:173], v[186:189], v[120:123]
	v_mfma_f32_16x16x32_bf16 v[112:115], v[178:181], v[186:189], v[112:115]
	v_mfma_f32_16x16x32_bf16 v[104:107], v[170:173], v[198:201], v[104:107]
	v_mfma_f32_16x16x32_bf16 v[96:99], v[178:181], v[198:201], v[96:99]
	v_mfma_f32_16x16x32_bf16 v[88:91], v[170:173], v[206:209], v[88:91]
	v_mfma_f32_16x16x32_bf16 v[80:83], v[178:181], v[206:209], v[80:83]
	v_mfma_f32_16x16x32_bf16 v[72:75], v[170:173], v[214:217], v[72:75]
	v_mfma_f32_16x16x32_bf16 v[64:67], v[178:181], v[214:217], v[64:67]
	v_mfma_f32_16x16x32_bf16 v[120:123], v[174:177], v[190:193], v[120:123]
	v_mfma_f32_16x16x32_bf16 v[112:115], v[182:185], v[190:193], v[112:115]
	v_mfma_f32_16x16x32_bf16 v[104:107], v[174:177], v[202:205], v[104:107]
	v_mfma_f32_16x16x32_bf16 v[96:99], v[182:185], v[202:205], v[96:99]
	v_mfma_f32_16x16x32_bf16 v[88:91], v[174:177], v[210:213], v[88:91]
	v_mfma_f32_16x16x32_bf16 v[80:83], v[182:185], v[210:213], v[80:83]
	v_mfma_f32_16x16x32_bf16 v[72:75], v[174:177], v[218:221], v[72:75]
	v_mfma_f32_16x16x32_bf16 v[64:67], v[182:185], v[218:221], v[64:67]
	s_barrier
	s_add_i32 s68, s58, s50
	s_add_u32 s98, s38, s8
	s_addc_u32 s99, s39, s9
	s_add_u32 s100, s42, s8
	s_addc_u32 s101, s43, s9
	s_mov_b32 m0, s68
	ds_read_b128 v[186:189], v152 offset:16384
	ds_read_b128 v[190:193], v152 offset:17408
	ds_read_b128 v[198:201], v152 offset:18432
	ds_read_b128 v[202:205], v152 offset:19456
	ds_read_b128 v[206:209], v152 offset:20480
	ds_read_b128 v[210:213], v152 offset:21504
	ds_read_b128 v[214:217], v152 offset:22528
	ds_read_b128 v[218:221], v152 offset:23552
	global_load_lds_dwordx4 v132, s[38:39]
	s_add_i32 m0, s68, 0x2000
	s_add_u32 s68, s38, 0x40000
	s_addc_u32 s69, s39, 0
	s_add_i32 s70, s59, s50
	global_load_lds_dwordx4 v128, s[38:39]
	s_mov_b32 m0, s70
	s_nop 0
	global_load_lds_dwordx4 v132, s[68:69]
	s_add_i32 m0, s70, 0x2000
	s_nop 0
	global_load_lds_dwordx4 v128, s[68:69]
	s_mov_b32 m0, s35
	s_nop 0
	global_load_lds_dwordx4 v134, s[42:43]
	s_mov_b32 m0, s52
	s_nop 0
	global_load_lds_dwordx4 v130, s[42:43]
	s_waitcnt vmcnt(8)
	s_waitcnt lgkmcnt(0)
	s_barrier
	v_mfma_f32_16x16x32_bf16 v[60:63], v[154:157], v[186:189], v[60:63]
	v_mfma_f32_16x16x32_bf16 v[52:55], v[162:165], v[186:189], v[52:55]
	v_mfma_f32_16x16x32_bf16 v[44:47], v[154:157], v[198:201], v[44:47]
	v_mfma_f32_16x16x32_bf16 v[36:39], v[162:165], v[198:201], v[36:39]
	v_mfma_f32_16x16x32_bf16 v[28:31], v[154:157], v[206:209], v[28:31]
	v_mfma_f32_16x16x32_bf16 v[20:23], v[162:165], v[206:209], v[20:23]
	v_mfma_f32_16x16x32_bf16 v[12:15], v[154:157], v[214:217], v[12:15]
	v_mfma_f32_16x16x32_bf16 v[4:7], v[162:165], v[214:217], v[4:7]
	v_mfma_f32_16x16x32_bf16 v[60:63], v[158:161], v[190:193], v[60:63]
	v_mfma_f32_16x16x32_bf16 v[52:55], v[166:169], v[190:193], v[52:55]
	v_mfma_f32_16x16x32_bf16 v[44:47], v[158:161], v[202:205], v[44:47]
	v_mfma_f32_16x16x32_bf16 v[36:39], v[166:169], v[202:205], v[36:39]
	v_mfma_f32_16x16x32_bf16 v[28:31], v[158:161], v[210:213], v[28:31]
	v_mfma_f32_16x16x32_bf16 v[20:23], v[166:169], v[210:213], v[20:23]
	v_mfma_f32_16x16x32_bf16 v[12:15], v[158:161], v[218:221], v[12:15]
	v_mfma_f32_16x16x32_bf16 v[4:7], v[166:169], v[218:221], v[4:7]
	v_mfma_f32_16x16x32_bf16 v[56:59], v[170:173], v[186:189], v[56:59]
	v_mfma_f32_16x16x32_bf16 v[48:51], v[178:181], v[186:189], v[48:51]
	v_mfma_f32_16x16x32_bf16 v[40:43], v[170:173], v[198:201], v[40:43]
	v_mfma_f32_16x16x32_bf16 v[32:35], v[178:181], v[198:201], v[32:35]
	v_mfma_f32_16x16x32_bf16 v[24:27], v[170:173], v[206:209], v[24:27]
	v_mfma_f32_16x16x32_bf16 v[16:19], v[178:181], v[206:209], v[16:19]
	v_mfma_f32_16x16x32_bf16 v[8:11], v[170:173], v[214:217], v[8:11]
	v_mfma_f32_16x16x32_bf16 v[0:3], v[178:181], v[214:217], v[0:3]
	v_mfma_f32_16x16x32_bf16 v[56:59], v[174:177], v[190:193], v[56:59]
	v_mfma_f32_16x16x32_bf16 v[48:51], v[182:185], v[190:193], v[48:51]
	v_mfma_f32_16x16x32_bf16 v[40:43], v[174:177], v[202:205], v[40:43]
	v_mfma_f32_16x16x32_bf16 v[32:35], v[182:185], v[202:205], v[32:35]
	v_mfma_f32_16x16x32_bf16 v[24:27], v[174:177], v[210:213], v[24:27]
	v_mfma_f32_16x16x32_bf16 v[16:19], v[182:185], v[210:213], v[16:19]
	v_mfma_f32_16x16x32_bf16 v[8:11], v[174:177], v[218:221], v[8:11]
	v_mfma_f32_16x16x32_bf16 v[0:3], v[182:185], v[218:221], v[0:3]
	s_barrier
; #define PG8_STAGE(bufoff, gbase, voff) do { _Pragma("unroll") for (int _i = 0; _i < 2; ++_i) \
;         __builtin_amdgcn_global_load_lds((const unsigned*)((const char*)(gbase) + (voff)[_i]), (PG8_LAS unsigned*)(lds + (bufoff) + ldsw + _i * 8192), 16, 0, 0); } while (0)
; #define PG8_LDA(dst, b, h) do { _Pragma("unroll") for (int m = 0; m < 4; ++m) _Pragma("unroll") for (int k = 0; k < 2; ++k) dst[m][k] = *(const PG8_LAS bf16x8*)(lds + PG8_SA(b, h) + aoff + m * 2048 + k * 1024); } while (0)
; #define PG8_LDB(dst, b, h) do { _Pragma("unroll") for (int n = 0; n < 2; ++n) _Pragma("unroll") for (int k = 0; k < 2; ++k) dst[n][k] = *(const PG8_LAS bf16x8*)(lds + PG8_SB(b, h) + boff + n * 2048 + k * 1024); } while (0)
; #define PG8_MMA(ai, bj, At, Bt) do { __builtin_amdgcn_s_setprio(1); _Pragma("unroll") for (int m = 0; m < 4; ++m) _Pragma("unroll") for (int n = 0; n < 2; ++n) _Pragma("unroll") for (int k = 0; k < 2; ++k) \
;         acc[ai][bj][m][n] = __builtin_amdgcn_mfma_f32_16x16x32_bf16(Bt[n][k], At[m][k], acc[ai][bj][m][n], 0, 0, 0); __builtin_amdgcn_s_setprio(0); } while (0)
; #define PG8_WAIT_V(n) asm volatile("s_waitcnt vmcnt(" #n ")" ::: "memory")
; #define PG8_WAIT_L(n) asm volatile("s_waitcnt lgkmcnt(" #n ")" ::: "memory")
; #define PG8_BAR __builtin_amdgcn_s_barrier()
; #define PG8_SCHED __builtin_amdgcn_sched_barrier(0)
; template <class Epi, class Sched, bool ALIGN_EPI = false, bool SP2 = false>
; __device__ __forceinline__ void gemm_phase(PG8_LAS unsigned char* lds, const Gemm g, const Sched& S, const Epi& E) {
;     ...
;             PG8_LDB(B0, 1, 0); PG8_LDB(B1, 1, 1); PG8_SCHED; PG8_LDA(At, 1, 0); PG8_STAGE(PG8_SA(0, 1), a2 + hstep, voffA);
;             PG8_WAIT_V(8); PG8_WAIT_L(0); PG8_BAR; PG8_MMA(0, 0, At, B0); PG8_MMA(0, 1, At, B1); PG8_BAR; PG8_SCHED;
;             PG8_LDA(At, 1, 1); PG8_STAGE(PG8_SB(1, 0), b3, voffB); PG8_STAGE(PG8_SB(1, 1), b3 + hstep, voffB); PG8_STAGE(PG8_SA(1, 0), a3, voffA);
;             PG8_WAIT_V(8); PG8_WAIT_L(0); PG8_BAR; PG8_MMA(1, 0, At, B0); PG8_MMA(1, 1, At, B1); PG8_BAR; PG8_SCHED;
	s_add_i32 s68, 0, 0x18000
	v_add_u32_e32 v153, s68, v147
	s_add_i32 s69, 0, 0x1c000
	ds_read_b128 v[154:157], v153
	ds_read_b128 v[158:161], v153 offset:1024
	ds_read_b128 v[162:165], v153 offset:2048
	ds_read_b128 v[166:169], v153 offset:3072
	v_add_u32_e32 v153, s69, v147
	ds_read_b128 v[170:173], v153
	ds_read_b128 v[174:177], v153 offset:1024
	ds_read_b128 v[178:181], v153 offset:2048
	ds_read_b128 v[182:185], v153 offset:3072
	s_add_u32 s42, s42, 0x40000
	s_addc_u32 s43, s43, 0
	s_mov_b32 m0, s53
	ds_read_b128 v[186:189], v152 offset:32768
	ds_read_b128 v[190:193], v152 offset:33792
	ds_read_b128 v[198:201], v152 offset:34816
	ds_read_b128 v[202:205], v152 offset:35840
	ds_read_b128 v[206:209], v152 offset:36864
	ds_read_b128 v[210:213], v152 offset:37888
	ds_read_b128 v[214:217], v152 offset:38912
	ds_read_b128 v[218:221], v152 offset:39936
	global_load_lds_dwordx4 v134, s[42:43]
	s_mov_b32 m0, s54
	s_nop 0
	global_load_lds_dwordx4 v130, s[42:43]
	s_waitcnt vmcnt(8)
	s_waitcnt lgkmcnt(0)
	s_barrier
	v_mfma_f32_16x16x32_bf16 v[124:127], v[154:157], v[186:189], v[124:127]
	v_mfma_f32_16x16x32_bf16 v[116:119], v[162:165], v[186:189], v[116:119]
	v_mfma_f32_16x16x32_bf16 v[108:111], v[154:157], v[198:201], v[108:111]
	v_mfma_f32_16x16x32_bf16 v[100:103], v[162:165], v[198:201], v[100:103]
	v_mfma_f32_16x16x32_bf16 v[92:95], v[154:157], v[206:209], v[92:95]
	v_mfma_f32_16x16x32_bf16 v[84:87], v[162:165], v[206:209], v[84:87]
	v_mfma_f32_16x16x32_bf16 v[76:79], v[154:157], v[214:217], v[76:79]
	v_mfma_f32_16x16x32_bf16 v[68:71], v[162:165], v[214:217], v[68:71]
	v_mfma_f32_16x16x32_bf16 v[124:127], v[158:161], v[190:193], v[124:127]
	v_mfma_f32_16x16x32_bf16 v[116:119], v[166:169], v[190:193], v[116:119]
	v_mfma_f32_16x16x32_bf16 v[108:111], v[158:161], v[202:205], v[108:111]
	v_mfma_f32_16x16x32_bf16 v[100:103], v[166:169], v[202:205], v[100:103]
	v_mfma_f32_16x16x32_bf16 v[92:95], v[158:161], v[210:213], v[92:95]
	v_mfma_f32_16x16x32_bf16 v[84:87], v[166:169], v[210:213], v[84:87]
	v_mfma_f32_16x16x32_bf16 v[76:79], v[158:161], v[218:221], v[76:79]
	v_mfma_f32_16x16x32_bf16 v[68:71], v[166:169], v[218:221], v[68:71]
	v_mfma_f32_16x16x32_bf16 v[120:123], v[170:173], v[186:189], v[120:123]
	v_mfma_f32_16x16x32_bf16 v[112:115], v[178:181], v[186:189], v[112:115]
	v_mfma_f32_16x16x32_bf16 v[104:107], v[170:173], v[198:201], v[104:107]
	v_mfma_f32_16x16x32_bf16 v[96:99], v[178:181], v[198:201], v[96:99]
	v_mfma_f32_16x16x32_bf16 v[88:91], v[170:173], v[206:209], v[88:91]
	v_mfma_f32_16x16x32_bf16 v[80:83], v[178:181], v[206:209], v[80:83]
	v_mfma_f32_16x16x32_bf16 v[72:75], v[170:173], v[214:217], v[72:75]
	v_mfma_f32_16x16x32_bf16 v[64:67], v[178:181], v[214:217], v[64:67]
	v_mfma_f32_16x16x32_bf16 v[120:123], v[174:177], v[190:193], v[120:123]
	v_mfma_f32_16x16x32_bf16 v[112:115], v[182:185], v[190:193], v[112:115]
	v_mfma_f32_16x16x32_bf16 v[104:107], v[174:177], v[202:205], v[104:107]
	v_mfma_f32_16x16x32_bf16 v[96:99], v[182:185], v[202:205], v[96:99]
	v_mfma_f32_16x16x32_bf16 v[88:91], v[174:177], v[210:213], v[88:91]
	v_mfma_f32_16x16x32_bf16 v[80:83], v[182:185], v[210:213], v[80:83]
	v_mfma_f32_16x16x32_bf16 v[72:75], v[174:177], v[218:221], v[72:75]
	v_mfma_f32_16x16x32_bf16 v[64:67], v[182:185], v[218:221], v[64:67]
	s_barrier
	s_add_i32 s42, s68, s50
	s_mov_b32 m0, s42
	ds_read_b128 v[186:189], v152 offset:49152
	ds_read_b128 v[190:193], v152 offset:50176
	ds_read_b128 v[198:201], v152 offset:51200
	ds_read_b128 v[202:205], v152 offset:52224
	ds_read_b128 v[206:209], v152 offset:53248
	ds_read_b128 v[210:213], v152 offset:54272
	ds_read_b128 v[214:217], v152 offset:55296
	ds_read_b128 v[218:221], v152 offset:56320
	global_load_lds_dwordx4 v132, s[98:99]
	s_add_i32 m0, s42, 0x2000
	s_add_u32 s38, s38, 0x40080
	s_addc_u32 s39, s39, 0
	s_add_i32 s42, s69, s50
	global_load_lds_dwordx4 v128, s[98:99]
	s_mov_b32 m0, s42
	s_nop 0
	global_load_lds_dwordx4 v132, s[38:39]
	s_add_i32 m0, s42, 0x2000
	s_nop 0
	global_load_lds_dwordx4 v128, s[38:39]
	s_mov_b32 m0, s56
	s_nop 0
	global_load_lds_dwordx4 v134, s[100:101]
	s_mov_b32 m0, s57
	s_nop 0
	global_load_lds_dwordx4 v130, s[100:101]
	s_waitcnt vmcnt(8)
	s_waitcnt lgkmcnt(0)
	s_barrier
	v_mfma_f32_16x16x32_bf16 v[60:63], v[154:157], v[186:189], v[60:63]
	v_mfma_f32_16x16x32_bf16 v[52:55], v[162:165], v[186:189], v[52:55]
	v_mfma_f32_16x16x32_bf16 v[44:47], v[154:157], v[198:201], v[44:47]
	v_mfma_f32_16x16x32_bf16 v[36:39], v[162:165], v[198:201], v[36:39]
	v_mfma_f32_16x16x32_bf16 v[28:31], v[154:157], v[206:209], v[28:31]
	v_mfma_f32_16x16x32_bf16 v[20:23], v[162:165], v[206:209], v[20:23]
	v_mfma_f32_16x16x32_bf16 v[12:15], v[154:157], v[214:217], v[12:15]
	v_mfma_f32_16x16x32_bf16 v[4:7], v[162:165], v[214:217], v[4:7]
	v_mfma_f32_16x16x32_bf16 v[60:63], v[158:161], v[190:193], v[60:63]
	v_mfma_f32_16x16x32_bf16 v[52:55], v[166:169], v[190:193], v[52:55]
	v_mfma_f32_16x16x32_bf16 v[44:47], v[158:161], v[202:205], v[44:47]
	v_mfma_f32_16x16x32_bf16 v[36:39], v[166:169], v[202:205], v[36:39]
	v_mfma_f32_16x16x32_bf16 v[28:31], v[158:161], v[210:213], v[28:31]
	v_mfma_f32_16x16x32_bf16 v[20:23], v[166:169], v[210:213], v[20:23]
	v_mfma_f32_16x16x32_bf16 v[12:15], v[158:161], v[218:221], v[12:15]
	v_mfma_f32_16x16x32_bf16 v[4:7], v[166:169], v[218:221], v[4:7]
	v_mfma_f32_16x16x32_bf16 v[56:59], v[170:173], v[186:189], v[56:59]
	v_mfma_f32_16x16x32_bf16 v[48:51], v[178:181], v[186:189], v[48:51]
	v_mfma_f32_16x16x32_bf16 v[40:43], v[170:173], v[198:201], v[40:43]
	v_mfma_f32_16x16x32_bf16 v[32:35], v[178:181], v[198:201], v[32:35]
	v_mfma_f32_16x16x32_bf16 v[24:27], v[170:173], v[206:209], v[24:27]
	v_mfma_f32_16x16x32_bf16 v[16:19], v[178:181], v[206:209], v[16:19]
	v_mfma_f32_16x16x32_bf16 v[8:11], v[170:173], v[214:217], v[8:11]
	v_mfma_f32_16x16x32_bf16 v[0:3], v[178:181], v[214:217], v[0:3]
	v_mfma_f32_16x16x32_bf16 v[56:59], v[174:177], v[190:193], v[56:59]
	v_mfma_f32_16x16x32_bf16 v[48:51], v[182:185], v[190:193], v[48:51]
	v_mfma_f32_16x16x32_bf16 v[40:43], v[174:177], v[202:205], v[40:43]
	v_mfma_f32_16x16x32_bf16 v[32:35], v[182:185], v[202:205], v[32:35]
	v_mfma_f32_16x16x32_bf16 v[24:27], v[174:177], v[210:213], v[24:27]
	v_mfma_f32_16x16x32_bf16 v[16:19], v[182:185], v[210:213], v[16:19]
	v_mfma_f32_16x16x32_bf16 v[8:11], v[174:177], v[218:221], v[8:11]
	v_mfma_f32_16x16x32_bf16 v[0:3], v[182:185], v[218:221], v[0:3]
	s_cmp_eq_u32 s67, 12
	s_cbranch_scc1 .Lxl_12
	s_barrier
	s_add_i32 s67, s67, 2
	s_add_u32 s20, s20, 0x100
	s_addc_u32 s21, s21, 0
	s_add_u32 s65, s65, 0x100
	s_addc_u32 s66, s66, 0
	s_cmp_gt_u32 s67, 13
	s_cbranch_scc0 .LBB0_1740
